# FFN-in epilogue token conv: 128 ds_bpermute_b32 neighbour-row fetches replaced by v_mov_b32_dpp row_ror:1/15 (DPP instead of LDS round trips); lgkmcnt waits in the region made full
# speedup vs baseline: 1.0042x; 1.0042x over previous
;     __device__ __forceinline__ void operator()(f32x4 (&acc)[2][2][4][2], const Unit& u, int wr, int wc, int fr, int fq) const {
;     ...
;         asm volatile("s_waitcnt lgkmcnt(0)" ::: "memory"); __builtin_amdgcn_s_barrier(); asm volatile("" ::: "memory");
;         const int lprev = (lane & 48) | ((fr + 15) & 15), lnext = (lane & 48) | ((fr + 1) & 15);
;         const int colg = u.pn * 128 + colw;
;         const bool f0 = (fr == 0), f15 = (fr == 15);
; #pragma unroll
;         for (int ai = 0; ai < 2; ++ai) { const int blk = 2 * ai + wr;
; #pragma unroll
;             for (int n = 0; n < 2; ++n) {
;                 const f32x4 w0v = *(const f32x4*)(cw + colg + 4 * n), w1v = *(const f32x4*)(cw + FFN + colg + 4 * n), w2v = *(const f32x4*)(cw + 2 * FFN + colg + 4 * n), cbv = *(const f32x4*)(cb + colg + 4 * n);
;                 f32x4 res[4];
; #pragma unroll
;                 for (int p = 0; p < 2; ++p) {
;                     const f32x2 w0 = {w0v[2 * p], w0v[2 * p + 1]}, w1 = {w1v[2 * p], w1v[2 * p + 1]}, w2 = {w2v[2 * p], w2v[2 * p + 1]}, bb = {cbv[2 * p], cbv[2 * p + 1]};
;                     f32x2 c[4], ps[4], ns[4];
; #pragma unroll
;                     for (int m = 0; m < 4; ++m) { c[m] = (f32x2){acc[ai][0][m][n][2 * p], acc[ai][0][m][n][2 * p + 1]};
;                         ps[m] = (f32x2){__shfl(c[m].x, lprev), __shfl(c[m].y, lprev)}; ns[m] = (f32x2){__shfl(c[m].x, lnext), __shfl(c[m].y, lnext)}; }
;                     f32x2 pe = {0.f, 0.f}, ne = {0.f, 0.f};
;                     if (blk > 0) pe = (f32x2){edgeL[(blk - 1) * 128 + colw + 4 * n + 2 * p], edgeL[(blk - 1) * 128 + colw + 4 * n + 2 * p + 1]};
;                     if (blk < 3) ne = (f32x2){edgeF[(blk + 1) * 128 + colw + 4 * n + 2 * p], edgeF[(blk + 1) * 128 + colw + 4 * n + 2 * p + 1]};
.LBB0_427:
	s_or_b64 exec, exec, s[66:67]
	v_lshl_or_b32 v162, s23, 7, v207
	v_ashrrev_i32_e32 v163, 31, v162
	v_readlane_b32 s12, v255, 32
	v_lshlrev_b64 v[138:139], 2, v[162:163]
	v_readlane_b32 s13, v255, 33
	s_waitcnt lgkmcnt(0)
	s_barrier
	v_mul_f32_e32 v146, 0x4b800000, v184
	v_lshl_add_u64 v[166:167], s[12:13], 0, v[138:139]
	v_readlane_b32 s12, v255, 30
	v_readlane_b32 s13, v255, 31
	v_cndmask_b32_e32 v146, v184, v146, vcc
	v_rsq_f32_e32 v146, v146
	v_lshl_add_u64 v[178:179], s[12:13], 0, v[138:139]
	v_readlane_b32 s12, v255, 34
	v_readlane_b32 s13, v255, 35
	global_load_dwordx4 v[126:129], v[166:167], off
	global_load_dwordx4 v[134:137], v[178:179], off
	v_lshl_add_u64 v[180:181], s[12:13], 0, v[138:139]
	v_readlane_b32 s12, v255, 20
	v_readlane_b32 s13, v255, 21
	global_load_dwordx4 v[130:133], v[180:181], off
	v_mul_f32_e32 v147, 0x4b800000, v187
	v_lshl_add_u64 v[168:169], s[12:13], 0, v[138:139]
	global_load_dwordx4 v[138:141], v[168:169], off
	v_cndmask_b32_e64 v147, v187, v147, s[62:63]
	v_rsq_f32_e32 v147, v147
	v_mul_f32_e32 v171, 0x45800000, v146
	v_cndmask_b32_e32 v184, v146, v171, vcc
	v_pk_mul_f32 v[188:189], v[102:103], v[184:185] op_sel_hi:[1,0]
	v_mul_f32_e32 v102, 0x45800000, v147
	v_cndmask_b32_e64 v102, v147, v102, s[62:63]
	v_pk_mul_f32 v[186:187], v[98:99], v[102:103] op_sel_hi:[1,0]
	v_or_b32_e32 v98, v208, v190
	v_lshlrev_b32_e32 v171, 2, v98
	v_or_b32_e32 v98, v209, v190
	v_lshlrev_b32_e32 v173, 2, v98
	v_mov_b32_dpp v103, v142 row_ror:1 row_mask:0xf bank_mask:0xf
	v_mov_b32_dpp v240, v143 row_ror:1 row_mask:0xf bank_mask:0xf
	v_mov_b32_dpp v185, v142 row_ror:15 row_mask:0xf bank_mask:0xf
	v_mov_b32_dpp v247, v143 row_ror:15 row_mask:0xf bank_mask:0xf
	v_mov_b32_dpp v232, v188 row_ror:1 row_mask:0xf bank_mask:0xf
	v_mov_b32_dpp v233, v189 row_ror:1 row_mask:0xf bank_mask:0xf
	v_mov_b32_dpp v241, v188 row_ror:15 row_mask:0xf bank_mask:0xf
	v_mov_b32_dpp v242, v189 row_ror:15 row_mask:0xf bank_mask:0xf
	v_mov_b32_dpp v146, v186 row_ror:1 row_mask:0xf bank_mask:0xf
	v_mov_b32_dpp v147, v187 row_ror:1 row_mask:0xf bank_mask:0xf
	v_mov_b32_dpp v234, v186 row_ror:15 row_mask:0xf bank_mask:0xf
	v_mov_b32_dpp v235, v187 row_ror:15 row_mask:0xf bank_mask:0xf
	v_mov_b32_dpp v223, v118 row_ror:1 row_mask:0xf bank_mask:0xf
	v_mov_b32_dpp v225, v119 row_ror:1 row_mask:0xf bank_mask:0xf
	v_mov_b32_dpp v174, v118 row_ror:15 row_mask:0xf bank_mask:0xf
	v_mov_b32_dpp v224, v119 row_ror:15 row_mask:0xf bank_mask:0xf
	v_cndmask_b32_e64 v99, 0, 1, s[82:83]
	v_mov_b32_e32 v183, v182
	v_mov_b32_e32 v177, v176
	v_mov_b32_e32 v165, v164
	v_mov_b32_e32 v161, v160
	v_mov_b32_e32 v98, 0
	v_cmp_ne_u32_e64 s[62:63], 1, v99
	s_andn2_b64 vcc, exec, s[82:83]
	v_mov_b32_e32 v192, 0
	v_mov_b32_e32 v193, 0
	s_cbranch_vccnz .LBB0_429
	ds_read_b64 v[192:193], v218

;     __device__ __forceinline__ void operator()(f32x4 (&acc)[2][2][4][2], const Unit& u, int wr, int wc, int fr, int fq) const {
;     ...
;                     for (int m = 0; m < 4; ++m) { c[m] = (f32x2){acc[ai][0][m][n][2 * p], acc[ai][0][m][n][2 * p + 1]};
;                         ps[m] = (f32x2){__shfl(c[m].x, lprev), __shfl(c[m].y, lprev)}; ns[m] = (f32x2){__shfl(c[m].x, lnext), __shfl(c[m].y, lnext)}; }
;                     f32x2 pe = {0.f, 0.f}, ne = {0.f, 0.f};
;                     if (blk > 0) pe = (f32x2){edgeL[(blk - 1) * 128 + colw + 4 * n + 2 * p], edgeL[(blk - 1) * 128 + colw + 4 * n + 2 * p + 1]};
;                     if (blk < 3) ne = (f32x2){edgeF[(blk + 1) * 128 + colw + 4 * n + 2 * p], edgeF[(blk + 1) * 128 + colw + 4 * n + 2 * p + 1]};
.LBB0_431:
	s_waitcnt lgkmcnt(0)
	v_pk_mul_f32 v[190:191], v[104:105], v[184:185] op_sel_hi:[1,0]
	v_pk_mul_f32 v[104:105], v[100:101], v[102:103] op_sel_hi:[1,0]
	v_mov_b32_dpp v243, v144 row_ror:1 row_mask:0xf bank_mask:0xf
	v_mov_b32_dpp v244, v145 row_ror:1 row_mask:0xf bank_mask:0xf
	v_mov_b32_dpp v248, v144 row_ror:15 row_mask:0xf bank_mask:0xf
	v_mov_b32_dpp v249, v145 row_ror:15 row_mask:0xf bank_mask:0xf
	v_mov_b32_dpp v236, v190 row_ror:1 row_mask:0xf bank_mask:0xf
	v_mov_b32_dpp v237, v191 row_ror:1 row_mask:0xf bank_mask:0xf
	v_mov_b32_dpp v245, v190 row_ror:15 row_mask:0xf bank_mask:0xf
	v_mov_b32_dpp v246, v191 row_ror:15 row_mask:0xf bank_mask:0xf
	v_mov_b32_dpp v226, v104 row_ror:1 row_mask:0xf bank_mask:0xf
	v_mov_b32_dpp v227, v105 row_ror:1 row_mask:0xf bank_mask:0xf
	v_mov_b32_dpp v238, v104 row_ror:15 row_mask:0xf bank_mask:0xf
	v_mov_b32_dpp v239, v105 row_ror:15 row_mask:0xf bank_mask:0xf
	v_mov_b32_dpp v229, v120 row_ror:1 row_mask:0xf bank_mask:0xf
	v_mov_b32_dpp v231, v121 row_ror:1 row_mask:0xf bank_mask:0xf
	v_mov_b32_dpp v228, v120 row_ror:15 row_mask:0xf bank_mask:0xf
	v_mov_b32_dpp v230, v121 row_ror:15 row_mask:0xf bank_mask:0xf
	v_mov_b32_e32 v100, 0
	s_and_b64 vcc, exec, s[62:63]
	v_mov_b32_e32 v194, 0
	v_mov_b32_e32 v195, 0
	s_cbranch_vccnz .LBB0_433
	ds_read_b64 v[194:195], v218 offset:8

; __device__ __forceinline__ unsigned cvt_pk_bf16(float lo, float hi) { return pk2(lo, hi); }
;     __device__ __forceinline__ void operator()(f32x4 (&acc)[2][2][4][2], const Unit& u, int wr, int wc, int fr, int fq) const {
;     ...
; #pragma unroll
;                     for (int m = 0; m < 4; ++m) {
;                         const f32x2 pvm = f0 ? (m == 0 ? pe : ps[m == 0 ? 0 : m - 1]) : ps[m];
;                         const f32x2 nvm = f15 ? (m == 3 ? ne : ns[m == 3 ? 3 : m + 1]) : ns[m];
;                         f32x2 cu = w1 * c[m] + bb; cu = w0 * pvm + cu; cu = w2 * nvm + cu;
;                         f32x2 tq = (cu * cu) * cu; tq = tq * 0.044715f + cu;
;                         const f32x2 ea = tq * (-2.3022082f);
;                         f32x2 dn; dn.x = __builtin_amdgcn_exp2f(ea.x); dn.y = __builtin_amdgcn_exp2f(ea.y); dn = dn + 1.0f;
;                         f32x2 rc; rc.x = __builtin_amdgcn_rcpf(dn.x); rc.y = __builtin_amdgcn_rcpf(dn.y);
;                         const f32x2 vv = {acc[ai][1][m][n][2 * p], acc[ai][1][m][n][2 * p + 1]};
;                         const f32x2 o = (cu * rc) * vv;
;                         res[m][2 * p] = o.x; res[m][2 * p + 1] = o.y; }
;                 }
; #pragma unroll
;                 for (int m = 0; m < 4; ++m) { const int j = ai * 128 + wr * 64 + m * 16 + fr;
;                     u32x2 w; w.x = cvt_pk_bf16(res[m][0], res[m][1]); w.y = cvt_pk_bf16(res[m][2], res[m][3]);
;                     if (j >= 1 && j <= 254) *(u32x2*)(act + (size_t)(rowt + j) * FFN + colg + 4 * n) = w; }
.LBB0_435:
	s_and_saveexec_b64 s[12:13], s[40:41]
	s_cbranch_execz .LBB0_437
	v_mov_b32_e32 v250, v182
	v_mov_b32_e32 v251, v182
	s_waitcnt lgkmcnt(0)
	v_cndmask_b32_e64 v193, v240, v193, s[36:37]
	v_cndmask_b32_e64 v192, v103, v192, s[36:37]
	s_waitcnt vmcnt(0)
	v_pk_fma_f32 v[142:143], v[142:143], v[134:135], v[138:139]
	v_pk_mul_f32 v[96:97], v[96:97], v[250:251]
	v_cndmask_b32_e64 v251, v247, v242, s[38:39]
	v_cndmask_b32_e64 v250, v185, v241, s[38:39]
	v_pk_fma_f32 v[142:143], v[126:127], v[192:193], v[142:143]
	s_mov_b32 s24, 0x3d372713
	v_pk_fma_f32 v[142:143], v[130:131], v[250:251], v[142:143]
	s_mov_b32 s66, 0xc0135761
	v_pk_mul_f32 v[192:193], v[142:143], v[142:143]
	v_pk_mul_f32 v[94:95], v[94:95], v[182:183]
	v_pk_mul_f32 v[192:193], v[142:143], v[192:193]
	v_pk_fma_f32 v[144:145], v[144:145], v[136:137], v[140:141]
	v_pk_fma_f32 v[192:193], v[192:193], s[24:25], v[142:143] op_sel_hi:[1,0,1]
	s_movk_i32 s15, 0x1600
	v_pk_mul_f32 v[192:193], v[192:193], s[66:67] op_sel_hi:[1,0]
	s_nop 0
	v_exp_f32_e32 v192, v192
	v_exp_f32_e32 v193, v193
	s_nop 0
	v_pk_add_f32 v[192:193], v[192:193], 1.0 op_sel_hi:[1,0]
	s_nop 0
	v_rcp_f32_e32 v192, v192
	v_rcp_f32_e32 v193, v193
	s_nop 0
	v_pk_mul_f32 v[142:143], v[142:143], v[192:193]
	s_nop 0
	v_pk_mul_f32 v[94:95], v[94:95], v[142:143]
	s_waitcnt lgkmcnt(0)
	v_cndmask_b32_e64 v143, v244, v195, s[36:37]
	v_cndmask_b32_e64 v142, v243, v194, s[36:37]
	v_pk_fma_f32 v[142:143], v[128:129], v[142:143], v[144:145]
	v_cndmask_b32_e64 v145, v249, v246, s[38:39]
	v_cndmask_b32_e64 v144, v248, v245, s[38:39]
	v_pk_fma_f32 v[142:143], v[132:133], v[144:145], v[142:143]
	s_nop 0
	v_pk_mul_f32 v[144:145], v[142:143], v[142:143]
	s_nop 0
	v_pk_mul_f32 v[144:145], v[142:143], v[144:145]
	s_nop 0
	v_pk_fma_f32 v[144:145], v[144:145], s[24:25], v[142:143] op_sel_hi:[1,0,1]
	s_nop 0
	v_pk_mul_f32 v[144:145], v[144:145], s[66:67] op_sel_hi:[1,0]
	s_nop 0
	v_exp_f32_e32 v144, v144
	v_exp_f32_e32 v145, v145
	s_nop 0
	v_pk_add_f32 v[144:145], v[144:145], 1.0 op_sel_hi:[1,0]
	s_nop 0
	v_rcp_f32_e32 v144, v144
	v_rcp_f32_e32 v145, v145
	s_nop 0
	v_pk_mul_f32 v[142:143], v[142:143], v[144:145]
	s_nop 0
	v_pk_mul_f32 v[96:97], v[96:97], v[142:143]
	s_nop 0
	v_cvt_pk_bf16_f32 v97, v96, v97
	v_cvt_pk_bf16_f32 v96, v94, v95
	v_mov_b64_e32 v[94:95], s[76:77]
	v_mad_i64_i32 v[94:95], s[66:67], v170, s15, v[94:95]
	v_lshl_add_u64 v[94:95], v[162:163], 1, v[94:95]
	global_store_dwordx2 v[94:95], v[96:97], off
.LBB0_437:
	s_or_b64 exec, exec, s[12:13]
	v_mov_b32_e32 v185, v184
	v_add_u32_e32 v142, s2, v210
	s_and_saveexec_b64 s[12:13], s[42:43]
	s_cbranch_execz .LBB0_439
	v_mov_b32_e32 v94, v184
	v_mov_b32_e32 v95, v184
	v_pk_mul_f32 v[88:89], v[88:89], v[94:95]
	s_waitcnt vmcnt(0)
	v_pk_fma_f32 v[94:95], v[190:191], v[136:137], v[140:141]
	s_waitcnt lgkmcnt(0)
	v_cndmask_b32_e64 v144, v236, v243, s[36:37]
	s_waitcnt lgkmcnt(0)
	v_cndmask_b32_e64 v145, v237, v244, s[36:37]
	v_pk_fma_f32 v[96:97], v[188:189], v[134:135], v[138:139]
	s_waitcnt lgkmcnt(0)
	v_cndmask_b32_e64 v188, v245, v238, s[38:39]
	s_waitcnt lgkmcnt(0)
	v_cndmask_b32_e64 v189, v246, v239, s[38:39]
	v_pk_fma_f32 v[94:95], v[128:129], v[144:145], v[94:95]
	s_mov_b32 s24, 0x3d372713
	v_pk_fma_f32 v[94:95], v[132:133], v[188:189], v[94:95]
	s_mov_b32 s66, 0xc0135761
	v_pk_mul_f32 v[144:145], v[94:95], v[94:95]
	v_pk_mul_f32 v[86:87], v[86:87], v[184:185]
	v_pk_mul_f32 v[144:145], v[94:95], v[144:145]
	s_movk_i32 s15, 0x1600
	v_pk_fma_f32 v[144:145], v[144:145], s[24:25], v[94:95] op_sel_hi:[1,0,1]
	s_nop 0
	v_pk_mul_f32 v[144:145], v[144:145], s[66:67] op_sel_hi:[1,0]
	s_nop 0
	v_exp_f32_e32 v144, v144
	v_exp_f32_e32 v145, v145
	s_nop 0
	v_pk_add_f32 v[144:145], v[144:145], 1.0 op_sel_hi:[1,0]
	s_nop 0
	v_rcp_f32_e32 v144, v144
	v_rcp_f32_e32 v145, v145
	s_nop 0
	v_pk_mul_f32 v[94:95], v[94:95], v[144:145]
	s_nop 0
	v_pk_mul_f32 v[88:89], v[88:89], v[94:95]
	v_cndmask_b32_e64 v94, v232, v103, s[36:37]
	v_cndmask_b32_e64 v95, v233, v240, s[36:37]
	v_cndmask_b32_e64 v144, v241, v234, s[38:39]
	v_cndmask_b32_e64 v145, v242, v235, s[38:39]
	v_pk_fma_f32 v[94:95], v[126:127], v[94:95], v[96:97]
	v_cvt_pk_bf16_f32 v89, v88, v89
	v_pk_fma_f32 v[94:95], v[130:131], v[144:145], v[94:95]
	s_nop 0
	v_pk_mul_f32 v[96:97], v[94:95], v[94:95]
	s_nop 0
	v_pk_mul_f32 v[96:97], v[94:95], v[96:97]
	s_nop 0
	v_pk_fma_f32 v[96:97], v[96:97], s[24:25], v[94:95] op_sel_hi:[1,0,1]
	s_nop 0
	v_pk_mul_f32 v[96:97], v[96:97], s[66:67] op_sel_hi:[1,0]
	s_nop 0
	v_exp_f32_e32 v96, v96
	v_exp_f32_e32 v97, v97
	s_nop 0
	v_pk_add_f32 v[96:97], v[96:97], 1.0 op_sel_hi:[1,0]
	s_nop 0
	v_rcp_f32_e32 v96, v96
	v_rcp_f32_e32 v97, v97
	s_nop 0
	v_pk_mul_f32 v[94:95], v[94:95], v[96:97]
	s_nop 0
	v_pk_mul_f32 v[86:87], v[86:87], v[94:95]
	s_nop 0
	v_cvt_pk_bf16_f32 v88, v86, v87
	v_mov_b64_e32 v[86:87], s[76:77]
	v_mad_i64_i32 v[86:87], s[66:67], v142, s15, v[86:87]
	v_lshl_add_u64 v[86:87], v[162:163], 1, v[86:87]
	global_store_dwordx2 v[86:87], v[88:89], off
;     __device__ __forceinline__ void operator()(f32x4 (&acc)[2][2][4][2], const Unit& u, int wr, int wc, int fr, int fq) const {
;     ...
;             for (int n = 0; n < 2; ++n) {
;                 const f32x4 w0v = *(const f32x4*)(cw + colg + 4 * n), w1v = *(const f32x4*)(cw + FFN + colg + 4 * n), w2v = *(const f32x4*)(cw + 2 * FFN + colg + 4 * n), cbv = *(const f32x4*)(cb + colg + 4 * n);
;                 f32x4 res[4];
; #pragma unroll
;                 for (int p = 0; p < 2; ++p) {
;                     const f32x2 w0 = {w0v[2 * p], w0v[2 * p + 1]}, w1 = {w1v[2 * p], w1v[2 * p + 1]}, w2 = {w2v[2 * p], w2v[2 * p + 1]}, bb = {cbv[2 * p], cbv[2 * p + 1]};
;                     f32x2 c[4], ps[4], ns[4];
; #pragma unroll
;                     for (int m = 0; m < 4; ++m) { c[m] = (f32x2){acc[ai][0][m][n][2 * p], acc[ai][0][m][n][2 * p + 1]};
;                         ps[m] = (f32x2){__shfl(c[m].x, lprev), __shfl(c[m].y, lprev)}; ns[m] = (f32x2){__shfl(c[m].x, lnext), __shfl(c[m].y, lnext)}; }
;                     f32x2 pe = {0.f, 0.f}, ne = {0.f, 0.f};
;                     if (blk > 0) pe = (f32x2){edgeL[(blk - 1) * 128 + colw + 4 * n + 2 * p], edgeL[(blk - 1) * 128 + colw + 4 * n + 2 * p + 1]};
;                     if (blk < 3) ne = (f32x2){edgeF[(blk + 1) * 128 + colw + 4 * n + 2 * p], edgeF[(blk + 1) * 128 + colw + 4 * n + 2 * p + 1]};
; #pragma unroll
;                     for (int m = 0; m < 4; ++m) {
;                         const f32x2 pvm = f0 ? (m == 0 ? pe : ps[m == 0 ? 0 : m - 1]) : ps[m];
;                         const f32x2 nvm = f15 ? (m == 3 ? ne : ns[m == 3 ? 3 : m + 1]) : ns[m];
;                         f32x2 cu = w1 * c[m] + bb; cu = w0 * pvm + cu; cu = w2 * nvm + cu;
;                         f32x2 tq = (cu * cu) * cu; tq = tq * 0.044715f + cu;
;                         const f32x2 ea = tq * (-2.3022082f);
;                         f32x2 dn; dn.x = __builtin_amdgcn_exp2f(ea.x); dn.y = __builtin_amdgcn_exp2f(ea.y); dn = dn + 1.0f;
;                         f32x2 rc; rc.x = __builtin_amdgcn_rcpf(dn.x); rc.y = __builtin_amdgcn_rcpf(dn.y);
;                         const f32x2 vv = {acc[ai][1][m][n][2 * p], acc[ai][1][m][n][2 * p + 1]};
;                         const f32x2 o = (cu * rc) * vv;
;                         res[m][2 * p] = o.x; res[m][2 * p + 1] = o.y; }
;                 }
; #pragma unroll
.LBB0_439:
	s_or_b64 exec, exec, s[12:13]
	v_mov_b32_e32 v103, v102
	v_add_u32_e32 v143, s2, v211
	s_and_saveexec_b64 s[12:13], s[44:45]
	s_cbranch_execz .LBB0_441
	v_mov_b32_e32 v86, v102
	v_mov_b32_e32 v87, v102
	v_pk_mul_f32 v[84:85], v[84:85], v[86:87]
	s_waitcnt vmcnt(0)
	v_pk_fma_f32 v[86:87], v[104:105], v[136:137], v[140:141]
	s_waitcnt lgkmcnt(0)
	v_cndmask_b32_e64 v94, v226, v236, s[36:37]
	s_waitcnt lgkmcnt(0)
	v_cndmask_b32_e64 v95, v227, v237, s[36:37]
	s_waitcnt lgkmcnt(0)
	v_cndmask_b32_e64 v96, v238, v228, s[38:39]
	s_waitcnt lgkmcnt(0)
	v_cndmask_b32_e64 v97, v239, v230, s[38:39]
	v_pk_fma_f32 v[86:87], v[128:129], v[94:95], v[86:87]
	s_mov_b32 s24, 0x3d372713
	v_pk_fma_f32 v[86:87], v[132:133], v[96:97], v[86:87]
	s_mov_b32 s66, 0xc0135761
	v_pk_mul_f32 v[94:95], v[86:87], v[86:87]
	v_pk_fma_f32 v[88:89], v[186:187], v[134:135], v[138:139]
	v_pk_mul_f32 v[94:95], v[86:87], v[94:95]
	v_pk_mul_f32 v[82:83], v[82:83], v[102:103]
	v_pk_fma_f32 v[94:95], v[94:95], s[24:25], v[86:87] op_sel_hi:[1,0,1]
	s_movk_i32 s15, 0x1600
	v_pk_mul_f32 v[94:95], v[94:95], s[66:67] op_sel_hi:[1,0]
	s_nop 0
	v_exp_f32_e32 v94, v94
	v_exp_f32_e32 v95, v95
	s_nop 0
	v_pk_add_f32 v[94:95], v[94:95], 1.0 op_sel_hi:[1,0]
	s_nop 0
	v_rcp_f32_e32 v94, v94
	v_rcp_f32_e32 v95, v95
	s_nop 0
	v_pk_mul_f32 v[86:87], v[86:87], v[94:95]
	s_nop 0
	v_pk_mul_f32 v[84:85], v[84:85], v[86:87]
	v_cndmask_b32_e64 v86, v146, v232, s[36:37]
	v_cndmask_b32_e64 v87, v147, v233, s[36:37]
	v_cndmask_b32_e64 v94, v234, v174, s[38:39]
	v_cndmask_b32_e64 v95, v235, v224, s[38:39]
	v_pk_fma_f32 v[86:87], v[126:127], v[86:87], v[88:89]
	v_cvt_pk_bf16_f32 v85, v84, v85
	v_pk_fma_f32 v[86:87], v[130:131], v[94:95], v[86:87]
	s_nop 0
	v_pk_mul_f32 v[88:89], v[86:87], v[86:87]
	s_nop 0
	v_pk_mul_f32 v[88:89], v[86:87], v[88:89]
	s_nop 0
	v_pk_fma_f32 v[88:89], v[88:89], s[24:25], v[86:87] op_sel_hi:[1,0,1]
	s_nop 0
	v_pk_mul_f32 v[88:89], v[88:89], s[66:67] op_sel_hi:[1,0]
	s_nop 0
	v_exp_f32_e32 v88, v88
	v_exp_f32_e32 v89, v89
	s_nop 0
	v_pk_add_f32 v[88:89], v[88:89], 1.0 op_sel_hi:[1,0]
	s_nop 0
	v_rcp_f32_e32 v88, v88
	v_rcp_f32_e32 v89, v89
	s_nop 0
	v_pk_mul_f32 v[86:87], v[86:87], v[88:89]
	s_nop 0
	v_pk_mul_f32 v[82:83], v[82:83], v[86:87]
	s_nop 0
	v_cvt_pk_bf16_f32 v84, v82, v83
	v_mov_b64_e32 v[82:83], s[76:77]
	v_mad_i64_i32 v[82:83], s[66:67], v143, s15, v[82:83]
	v_lshl_add_u64 v[82:83], v[162:163], 1, v[82:83]
	global_store_dwordx2 v[82:83], v[84:85], off
.LBB0_441:
	s_or_b64 exec, exec, s[12:13]
	v_add_u32_e32 v144, s2, v212
	s_and_saveexec_b64 s[12:13], s[46:47]
	s_cbranch_execz .LBB0_443
	v_mov_b32_e32 v82, v176
	v_mov_b32_e32 v83, v176
	v_pk_mul_f32 v[80:81], v[80:81], v[82:83]
	s_waitcnt vmcnt(0)
	v_pk_fma_f32 v[82:83], v[120:121], v[136:137], v[140:141]
	s_waitcnt lgkmcnt(0)
	v_cndmask_b32_e64 v87, v231, v227, s[36:37]
	v_cndmask_b32_e64 v86, v229, v226, s[36:37]
	s_waitcnt lgkmcnt(0)
	v_cndmask_b32_e64 v89, v230, v101, s[38:39]
	v_cndmask_b32_e64 v88, v228, v100, s[38:39]
	v_pk_fma_f32 v[82:83], v[128:129], v[86:87], v[82:83]
	s_mov_b32 s24, 0x3d372713
	v_pk_fma_f32 v[82:83], v[132:133], v[88:89], v[82:83]
	s_mov_b32 s66, 0xc0135761
	v_pk_mul_f32 v[86:87], v[82:83], v[82:83]
	v_pk_fma_f32 v[84:85], v[118:119], v[134:135], v[138:139]
	v_pk_mul_f32 v[86:87], v[82:83], v[86:87]
	v_pk_mul_f32 v[78:79], v[78:79], v[176:177]
	v_pk_fma_f32 v[86:87], v[86:87], s[24:25], v[82:83] op_sel_hi:[1,0,1]
	s_movk_i32 s15, 0x1600
	v_pk_mul_f32 v[86:87], v[86:87], s[66:67] op_sel_hi:[1,0]
	s_nop 0
	v_exp_f32_e32 v86, v86
	v_exp_f32_e32 v87, v87
	s_nop 0
	v_pk_add_f32 v[86:87], v[86:87], 1.0 op_sel_hi:[1,0]
	s_nop 0
	v_rcp_f32_e32 v86, v86
	v_rcp_f32_e32 v87, v87
	s_nop 0
	v_pk_mul_f32 v[82:83], v[82:83], v[86:87]
	s_nop 0
	v_pk_mul_f32 v[80:81], v[80:81], v[82:83]
	v_cndmask_b32_e64 v83, v225, v147, s[36:37]
	v_cndmask_b32_e64 v82, v223, v146, s[36:37]
	v_cndmask_b32_e64 v87, v224, v99, s[38:39]
	v_cndmask_b32_e64 v86, v174, v98, s[38:39]
	v_pk_fma_f32 v[82:83], v[126:127], v[82:83], v[84:85]
	v_cvt_pk_bf16_f32 v81, v80, v81
	v_pk_fma_f32 v[82:83], v[130:131], v[86:87], v[82:83]
	s_nop 0
	v_pk_mul_f32 v[84:85], v[82:83], v[82:83]
	s_nop 0
	v_pk_mul_f32 v[84:85], v[82:83], v[84:85]
	s_nop 0
	v_pk_fma_f32 v[84:85], v[84:85], s[24:25], v[82:83] op_sel_hi:[1,0,1]
	s_nop 0
	v_pk_mul_f32 v[84:85], v[84:85], s[66:67] op_sel_hi:[1,0]
	s_nop 0
	v_exp_f32_e32 v84, v84
	v_exp_f32_e32 v85, v85
	s_nop 0
	v_pk_add_f32 v[84:85], v[84:85], 1.0 op_sel_hi:[1,0]
	s_nop 0
	v_rcp_f32_e32 v84, v84
	v_rcp_f32_e32 v85, v85
	s_nop 0
	v_pk_mul_f32 v[82:83], v[82:83], v[84:85]
	s_nop 0
	v_pk_mul_f32 v[78:79], v[78:79], v[82:83]
	s_nop 0
	v_cvt_pk_bf16_f32 v80, v78, v79
	v_mov_b64_e32 v[78:79], s[76:77]
	v_mad_i64_i32 v[78:79], s[66:67], v144, s15, v[78:79]
	v_lshl_add_u64 v[78:79], v[162:163], 1, v[78:79]
	global_store_dwordx2 v[78:79], v[80:81], off
.LBB0_443:
	s_or_b64 exec, exec, s[12:13]
	v_add_co_u32_e32 v82, vcc, 0x2000, v166
	global_load_dwordx4 v[78:81], v[166:167], off offset:16
	s_nop 0
	v_addc_co_u32_e32 v83, vcc, 0, v167, vcc
	v_add_co_u32_e32 v84, vcc, 0x5000, v166
	s_waitcnt lgkmcnt(0)
	v_pk_mul_f32 v[98:99], v[70:71], v[184:185]
	v_addc_co_u32_e32 v85, vcc, 0, v167, vcc
	global_load_dwordx4 v[86:89], v[82:83], off offset:3088
	s_nop 0
	global_load_dwordx4 v[82:85], v[84:85], off offset:2064
	s_nop 0
	global_load_dwordx4 v[94:97], v[168:169], off offset:16
	v_pk_mul_f32 v[70:71], v[66:67], v[102:103]
	v_mov_b32_dpp v147, v122 row_ror:1 row_mask:0xf bank_mask:0xf
	v_mov_b32_dpp v174, v123 row_ror:1 row_mask:0xf bank_mask:0xf
	v_mov_b32_dpp v192, v122 row_ror:15 row_mask:0xf bank_mask:0xf
	v_mov_b32_dpp v193, v123 row_ror:15 row_mask:0xf bank_mask:0xf
	s_waitcnt vmcnt(6)
	v_mov_b32_dpp v136, v98 row_ror:1 row_mask:0xf bank_mask:0xf
	v_mov_b32_dpp v137, v99 row_ror:1 row_mask:0xf bank_mask:0xf
	v_mov_b32_dpp v186, v98 row_ror:15 row_mask:0xf bank_mask:0xf
	v_mov_b32_dpp v187, v99 row_ror:15 row_mask:0xf bank_mask:0xf
	v_mov_b32_dpp v120, v70 row_ror:1 row_mask:0xf bank_mask:0xf
	v_mov_b32_dpp v121, v71 row_ror:1 row_mask:0xf bank_mask:0xf
	s_waitcnt vmcnt(4)
	v_mov_b32_dpp v138, v70 row_ror:15 row_mask:0xf bank_mask:0xf
	v_mov_b32_dpp v139, v71 row_ror:15 row_mask:0xf bank_mask:0xf
	v_mov_b32_dpp v127, v114 row_ror:1 row_mask:0xf bank_mask:0xf
	v_mov_b32_dpp v129, v115 row_ror:1 row_mask:0xf bank_mask:0xf
	v_mov_b32_dpp v126, v114 row_ror:15 row_mask:0xf bank_mask:0xf
	v_mov_b32_dpp v128, v115 row_ror:15 row_mask:0xf bank_mask:0xf
	v_mov_b32_e32 v66, 0
	s_and_b64 vcc, exec, s[62:63]
	v_mov_b32_e32 v104, 0
	v_mov_b32_e32 v105, 0
	s_cbranch_vccnz .LBB0_445
	ds_read_b64 v[104:105], v218 offset:16

;     __device__ __forceinline__ void operator()(f32x4 (&acc)[2][2][4][2], const Unit& u, int wr, int wc, int fr, int fq) const {
;     ...
;                     for (int m = 0; m < 4; ++m) { c[m] = (f32x2){acc[ai][0][m][n][2 * p], acc[ai][0][m][n][2 * p + 1]};
;                         ps[m] = (f32x2){__shfl(c[m].x, lprev), __shfl(c[m].y, lprev)}; ns[m] = (f32x2){__shfl(c[m].x, lnext), __shfl(c[m].y, lnext)}; }
;                     f32x2 pe = {0.f, 0.f}, ne = {0.f, 0.f};
;                     if (blk > 0) pe = (f32x2){edgeL[(blk - 1) * 128 + colw + 4 * n + 2 * p], edgeL[(blk - 1) * 128 + colw + 4 * n + 2 * p + 1]};
;                     if (blk < 3) ne = (f32x2){edgeF[(blk + 1) * 128 + colw + 4 * n + 2 * p], edgeF[(blk + 1) * 128 + colw + 4 * n + 2 * p + 1]};
.LBB0_447:
	s_waitcnt lgkmcnt(0)
	v_mov_b32_e32 v100, v184
	v_mov_b32_e32 v101, v184
	v_pk_mul_f32 v[100:101], v[72:73], v[100:101]
	v_mov_b32_e32 v72, v102
	v_mov_b32_e32 v73, v102
	v_pk_mul_f32 v[72:73], v[68:69], v[72:73]
	v_mov_b32_dpp v188, v124 row_ror:1 row_mask:0xf bank_mask:0xf
	v_mov_b32_dpp v189, v125 row_ror:1 row_mask:0xf bank_mask:0xf
	v_mov_b32_dpp v194, v124 row_ror:15 row_mask:0xf bank_mask:0xf
	v_mov_b32_dpp v195, v125 row_ror:15 row_mask:0xf bank_mask:0xf
	v_mov_b32_dpp v140, v100 row_ror:1 row_mask:0xf bank_mask:0xf
	v_mov_b32_dpp v141, v101 row_ror:1 row_mask:0xf bank_mask:0xf
	v_mov_b32_dpp v190, v100 row_ror:15 row_mask:0xf bank_mask:0xf
	v_mov_b32_dpp v191, v101 row_ror:15 row_mask:0xf bank_mask:0xf
	v_mov_b32_dpp v130, v72 row_ror:1 row_mask:0xf bank_mask:0xf
	v_mov_b32_dpp v131, v73 row_ror:1 row_mask:0xf bank_mask:0xf
	v_mov_b32_dpp v145, v72 row_ror:15 row_mask:0xf bank_mask:0xf
	v_mov_b32_dpp v146, v73 row_ror:15 row_mask:0xf bank_mask:0xf
	v_mov_b32_dpp v133, v116 row_ror:1 row_mask:0xf bank_mask:0xf
	v_mov_b32_dpp v135, v117 row_ror:1 row_mask:0xf bank_mask:0xf
	v_mov_b32_dpp v132, v116 row_ror:15 row_mask:0xf bank_mask:0xf
	v_mov_b32_dpp v134, v117 row_ror:15 row_mask:0xf bank_mask:0xf
	v_mov_b32_e32 v68, 0
	s_and_b64 vcc, exec, s[62:63]
	v_mov_b32_e32 v118, 0
	v_mov_b32_e32 v119, 0
	s_cbranch_vccnz .LBB0_449
	ds_read_b64 v[118:119], v218 offset:24

; __device__ __forceinline__ unsigned cvt_pk_bf16(float lo, float hi) { return pk2(lo, hi); }
;     __device__ __forceinline__ void operator()(f32x4 (&acc)[2][2][4][2], const Unit& u, int wr, int wc, int fr, int fq) const {
;     ...
; #pragma unroll
;                     for (int m = 0; m < 4; ++m) {
;                         const f32x2 pvm = f0 ? (m == 0 ? pe : ps[m == 0 ? 0 : m - 1]) : ps[m];
;                         const f32x2 nvm = f15 ? (m == 3 ? ne : ns[m == 3 ? 3 : m + 1]) : ns[m];
;                         f32x2 cu = w1 * c[m] + bb; cu = w0 * pvm + cu; cu = w2 * nvm + cu;
;                         f32x2 tq = (cu * cu) * cu; tq = tq * 0.044715f + cu;
;                         const f32x2 ea = tq * (-2.3022082f);
;                         f32x2 dn; dn.x = __builtin_amdgcn_exp2f(ea.x); dn.y = __builtin_amdgcn_exp2f(ea.y); dn = dn + 1.0f;
;                         f32x2 rc; rc.x = __builtin_amdgcn_rcpf(dn.x); rc.y = __builtin_amdgcn_rcpf(dn.y);
;                         const f32x2 vv = {acc[ai][1][m][n][2 * p], acc[ai][1][m][n][2 * p + 1]};
;                         const f32x2 o = (cu * rc) * vv;
;                         res[m][2 * p] = o.x; res[m][2 * p + 1] = o.y; }
;                 }
; #pragma unroll
;                 for (int m = 0; m < 4; ++m) { const int j = ai * 128 + wr * 64 + m * 16 + fr;
;                     u32x2 w; w.x = cvt_pk_bf16(res[m][0], res[m][1]); w.y = cvt_pk_bf16(res[m][2], res[m][3]);
;                     if (j >= 1 && j <= 254) *(u32x2*)(act + (size_t)(rowt + j) * FFN + colg + 4 * n) = w; }
.LBB0_451:
	s_and_saveexec_b64 s[12:13], s[40:41]
	s_movk_i32 s64, 0x6000
	v_readlane_b32 s65, v255, 9
	s_cbranch_execz .LBB0_455
	s_waitcnt lgkmcnt(0)
	v_cndmask_b32_e64 v105, v174, v105, s[36:37]
	v_cndmask_b32_e64 v104, v147, v104, s[36:37]
	s_waitcnt vmcnt(0)
	v_pk_fma_f32 v[122:123], v[122:123], v[86:87], v[94:95]
	v_mov_b32_e32 v224, v182
	v_mov_b32_e32 v225, v182
	v_pk_mul_f32 v[62:63], v[62:63], v[182:183]
	v_cndmask_b32_e64 v183, v193, v187, s[38:39]
	v_cndmask_b32_e64 v182, v192, v186, s[38:39]
	v_pk_fma_f32 v[104:105], v[78:79], v[104:105], v[122:123]
	s_mov_b32 s24, 0x3d372713
	v_pk_fma_f32 v[104:105], v[82:83], v[182:183], v[104:105]
	s_mov_b32 s62, 0xc0135761
	v_pk_mul_f32 v[122:123], v[104:105], v[104:105]
	v_pk_fma_f32 v[124:125], v[124:125], v[88:89], v[96:97]
	v_pk_mul_f32 v[122:123], v[104:105], v[122:123]
	v_pk_mul_f32 v[64:65], v[64:65], v[224:225]
	v_pk_fma_f32 v[122:123], v[122:123], s[24:25], v[104:105] op_sel_hi:[1,0,1]
	s_movk_i32 s15, 0x1600
	v_pk_mul_f32 v[122:123], v[122:123], s[62:63] op_sel_hi:[1,0]
	s_nop 0
	v_exp_f32_e32 v122, v122
	v_exp_f32_e32 v123, v123
	s_nop 0
	v_pk_add_f32 v[122:123], v[122:123], 1.0 op_sel_hi:[1,0]
	s_nop 0
	v_rcp_f32_e32 v122, v122
	v_rcp_f32_e32 v123, v123
	s_nop 0
	v_pk_mul_f32 v[104:105], v[104:105], v[122:123]
	s_nop 0
	v_pk_mul_f32 v[62:63], v[62:63], v[104:105]
	s_waitcnt lgkmcnt(0)
	v_cndmask_b32_e64 v105, v189, v119, s[36:37]
	v_cndmask_b32_e64 v104, v188, v118, s[36:37]
	v_pk_fma_f32 v[104:105], v[80:81], v[104:105], v[124:125]
	v_cndmask_b32_e64 v119, v195, v191, s[38:39]
	v_cndmask_b32_e64 v118, v194, v190, s[38:39]
	v_pk_fma_f32 v[104:105], v[84:85], v[118:119], v[104:105]
	s_nop 0
	v_pk_mul_f32 v[118:119], v[104:105], v[104:105]
	s_nop 0
	v_pk_mul_f32 v[118:119], v[104:105], v[118:119]
	s_nop 0
	v_pk_fma_f32 v[118:119], v[118:119], s[24:25], v[104:105] op_sel_hi:[1,0,1]
	s_nop 0
	v_pk_mul_f32 v[118:119], v[118:119], s[62:63] op_sel_hi:[1,0]
	s_nop 0
	v_exp_f32_e32 v118, v118
	v_exp_f32_e32 v119, v119
	s_nop 0
	v_pk_add_f32 v[118:119], v[118:119], 1.0 op_sel_hi:[1,0]
	s_nop 0
	v_rcp_f32_e32 v118, v118
	v_rcp_f32_e32 v119, v119
	s_nop 0
	v_pk_mul_f32 v[104:105], v[104:105], v[118:119]
	s_nop 0
	v_pk_mul_f32 v[64:65], v[64:65], v[104:105]
	s_nop 0
	v_cvt_pk_bf16_f32 v65, v64, v65
	v_cvt_pk_bf16_f32 v64, v62, v63
	v_mov_b64_e32 v[62:63], s[76:77]
	v_mad_i64_i32 v[62:63], s[62:63], v170, s15, v[62:63]
	v_lshl_add_u64 v[62:63], v[162:163], 1, v[62:63]
	global_store_dwordx2 v[62:63], v[64:65], off offset:8
	s_or_b64 exec, exec, s[12:13]
	s_and_saveexec_b64 s[12:13], s[42:43]
	s_cbranch_execnz .LBB0_456

; __device__ __forceinline__ unsigned cvt_pk_bf16(float lo, float hi) { return pk2(lo, hi); }
;     __device__ __forceinline__ void operator()(f32x4 (&acc)[2][2][4][2], const Unit& u, int wr, int wc, int fr, int fq) const {
;     ...
;                     for (int m = 0; m < 4; ++m) { c[m] = (f32x2){acc[ai][0][m][n][2 * p], acc[ai][0][m][n][2 * p + 1]};
;                         ps[m] = (f32x2){__shfl(c[m].x, lprev), __shfl(c[m].y, lprev)}; ns[m] = (f32x2){__shfl(c[m].x, lnext), __shfl(c[m].y, lnext)}; }
;                     f32x2 pe = {0.f, 0.f}, ne = {0.f, 0.f};
;                     if (blk > 0) pe = (f32x2){edgeL[(blk - 1) * 128 + colw + 4 * n + 2 * p], edgeL[(blk - 1) * 128 + colw + 4 * n + 2 * p + 1]};
;                     if (blk < 3) ne = (f32x2){edgeF[(blk + 1) * 128 + colw + 4 * n + 2 * p], edgeF[(blk + 1) * 128 + colw + 4 * n + 2 * p + 1]};
; #pragma unroll
;                     for (int m = 0; m < 4; ++m) {
;                         const f32x2 pvm = f0 ? (m == 0 ? pe : ps[m == 0 ? 0 : m - 1]) : ps[m];
;                         const f32x2 nvm = f15 ? (m == 3 ? ne : ns[m == 3 ? 3 : m + 1]) : ns[m];
;                         f32x2 cu = w1 * c[m] + bb; cu = w0 * pvm + cu; cu = w2 * nvm + cu;
;                         f32x2 tq = (cu * cu) * cu; tq = tq * 0.044715f + cu;
;                         const f32x2 ea = tq * (-2.3022082f);
;                         f32x2 dn; dn.x = __builtin_amdgcn_exp2f(ea.x); dn.y = __builtin_amdgcn_exp2f(ea.y); dn = dn + 1.0f;
;                         f32x2 rc; rc.x = __builtin_amdgcn_rcpf(dn.x); rc.y = __builtin_amdgcn_rcpf(dn.y);
;                         const f32x2 vv = {acc[ai][1][m][n][2 * p], acc[ai][1][m][n][2 * p + 1]};
;                         const f32x2 o = (cu * rc) * vv;
;                         res[m][2 * p] = o.x; res[m][2 * p + 1] = o.y; }
;                 }
; #pragma unroll
;                 for (int m = 0; m < 4; ++m) { const int j = ai * 128 + wr * 64 + m * 16 + fr;
;                     u32x2 w; w.x = cvt_pk_bf16(res[m][0], res[m][1]); w.y = cvt_pk_bf16(res[m][2], res[m][3]);
;                     if (j >= 1 && j <= 254) *(u32x2*)(act + (size_t)(rowt + j) * FFN + colg + 4 * n) = w; }
.LBB0_454:
	v_mov_b32_e32 v58, v102
	v_mov_b32_e32 v59, v102
	v_pk_mul_f32 v[56:57], v[56:57], v[58:59]
	s_waitcnt vmcnt(0)
	v_pk_fma_f32 v[58:59], v[72:73], v[88:89], v[96:97]
	s_waitcnt lgkmcnt(0)
	v_cndmask_b32_e64 v62, v130, v140, s[36:37]
	s_waitcnt lgkmcnt(0)
	v_cndmask_b32_e64 v63, v131, v141, s[36:37]
	s_waitcnt lgkmcnt(0)
	v_cndmask_b32_e64 v64, v145, v132, s[38:39]
	s_waitcnt lgkmcnt(0)
	v_cndmask_b32_e64 v65, v146, v134, s[38:39]
	v_pk_fma_f32 v[58:59], v[80:81], v[62:63], v[58:59]
	s_mov_b32 s24, 0x3d372713
	v_pk_fma_f32 v[58:59], v[84:85], v[64:65], v[58:59]
	s_mov_b32 s62, 0xc0135761
	v_pk_mul_f32 v[62:63], v[58:59], v[58:59]
	v_pk_fma_f32 v[60:61], v[70:71], v[86:87], v[94:95]
	v_pk_mul_f32 v[62:63], v[58:59], v[62:63]
	v_pk_mul_f32 v[54:55], v[54:55], v[102:103]
	v_pk_fma_f32 v[62:63], v[62:63], s[24:25], v[58:59] op_sel_hi:[1,0,1]
	s_movk_i32 s15, 0x1600
	v_pk_mul_f32 v[62:63], v[62:63], s[62:63] op_sel_hi:[1,0]
	s_nop 0
	v_exp_f32_e32 v62, v62
	v_exp_f32_e32 v63, v63
	s_nop 0
	v_pk_add_f32 v[62:63], v[62:63], 1.0 op_sel_hi:[1,0]
	s_nop 0
	v_rcp_f32_e32 v62, v62
	v_rcp_f32_e32 v63, v63
	s_nop 0
	v_pk_mul_f32 v[58:59], v[58:59], v[62:63]
	s_nop 0
	v_pk_mul_f32 v[56:57], v[56:57], v[58:59]
	v_cndmask_b32_e64 v58, v120, v136, s[36:37]
	v_cndmask_b32_e64 v59, v121, v137, s[36:37]
	v_cndmask_b32_e64 v62, v138, v126, s[38:39]
	v_cndmask_b32_e64 v63, v139, v128, s[38:39]
	v_pk_fma_f32 v[58:59], v[78:79], v[58:59], v[60:61]
	v_cvt_pk_bf16_f32 v57, v56, v57
	v_pk_fma_f32 v[58:59], v[82:83], v[62:63], v[58:59]
	s_nop 0
	v_pk_mul_f32 v[60:61], v[58:59], v[58:59]
	s_nop 0
	v_pk_mul_f32 v[60:61], v[58:59], v[60:61]
	s_nop 0
	v_pk_fma_f32 v[60:61], v[60:61], s[24:25], v[58:59] op_sel_hi:[1,0,1]
	s_nop 0
	v_pk_mul_f32 v[60:61], v[60:61], s[62:63] op_sel_hi:[1,0]
	s_nop 0
	v_exp_f32_e32 v60, v60
	v_exp_f32_e32 v61, v61
	s_nop 0
	v_pk_add_f32 v[60:61], v[60:61], 1.0 op_sel_hi:[1,0]
	s_nop 0
	v_rcp_f32_e32 v60, v60
	v_rcp_f32_e32 v61, v61
	s_nop 0
	v_pk_mul_f32 v[58:59], v[58:59], v[60:61]
	s_nop 0
	v_pk_mul_f32 v[54:55], v[54:55], v[58:59]
	s_nop 0
	v_cvt_pk_bf16_f32 v56, v54, v55
	v_mov_b64_e32 v[54:55], s[76:77]
	v_mad_i64_i32 v[54:55], s[62:63], v143, s15, v[54:55]
	v_lshl_add_u64 v[54:55], v[162:163], 1, v[54:55]
	global_store_dwordx2 v[54:55], v[56:57], off offset:8
	s_or_b64 exec, exec, s[12:13]
	s_and_saveexec_b64 s[12:13], s[46:47]
	s_cbranch_execnz .LBB0_458
	s_branch .LBB0_459

; __device__ __forceinline__ unsigned cvt_pk_bf16(float lo, float hi) { return pk2(lo, hi); }
;     __device__ __forceinline__ void operator()(f32x4 (&acc)[2][2][4][2], const Unit& u, int wr, int wc, int fr, int fq) const {
;     ...
;                     for (int m = 0; m < 4; ++m) { c[m] = (f32x2){acc[ai][0][m][n][2 * p], acc[ai][0][m][n][2 * p + 1]};
;                         ps[m] = (f32x2){__shfl(c[m].x, lprev), __shfl(c[m].y, lprev)}; ns[m] = (f32x2){__shfl(c[m].x, lnext), __shfl(c[m].y, lnext)}; }
;                     f32x2 pe = {0.f, 0.f}, ne = {0.f, 0.f};
;                     if (blk > 0) pe = (f32x2){edgeL[(blk - 1) * 128 + colw + 4 * n + 2 * p], edgeL[(blk - 1) * 128 + colw + 4 * n + 2 * p + 1]};
;                     if (blk < 3) ne = (f32x2){edgeF[(blk + 1) * 128 + colw + 4 * n + 2 * p], edgeF[(blk + 1) * 128 + colw + 4 * n + 2 * p + 1]};
; #pragma unroll
;                     for (int m = 0; m < 4; ++m) {
;                         const f32x2 pvm = f0 ? (m == 0 ? pe : ps[m == 0 ? 0 : m - 1]) : ps[m];
;                         const f32x2 nvm = f15 ? (m == 3 ? ne : ns[m == 3 ? 3 : m + 1]) : ns[m];
;                         f32x2 cu = w1 * c[m] + bb; cu = w0 * pvm + cu; cu = w2 * nvm + cu;
;                         f32x2 tq = (cu * cu) * cu; tq = tq * 0.044715f + cu;
;                         const f32x2 ea = tq * (-2.3022082f);
;                         f32x2 dn; dn.x = __builtin_amdgcn_exp2f(ea.x); dn.y = __builtin_amdgcn_exp2f(ea.y); dn = dn + 1.0f;
;                         f32x2 rc; rc.x = __builtin_amdgcn_rcpf(dn.x); rc.y = __builtin_amdgcn_rcpf(dn.y);
;                         const f32x2 vv = {acc[ai][1][m][n][2 * p], acc[ai][1][m][n][2 * p + 1]};
;                         const f32x2 o = (cu * rc) * vv;
;                         res[m][2 * p] = o.x; res[m][2 * p + 1] = o.y; }
;                 }
; #pragma unroll
;                 for (int m = 0; m < 4; ++m) { const int j = ai * 128 + wr * 64 + m * 16 + fr;
;                     u32x2 w; w.x = cvt_pk_bf16(res[m][0], res[m][1]); w.y = cvt_pk_bf16(res[m][2], res[m][3]);
;                     if (j >= 1 && j <= 254) *(u32x2*)(act + (size_t)(rowt + j) * FFN + colg + 4 * n) = w; }
.LBB0_456:
	v_mov_b32_e32 v62, v184
	v_mov_b32_e32 v63, v184
	v_pk_mul_f32 v[60:61], v[60:61], v[62:63]
	s_waitcnt vmcnt(0)
	v_pk_fma_f32 v[62:63], v[100:101], v[88:89], v[96:97]
	v_pk_fma_f32 v[64:65], v[98:99], v[86:87], v[94:95]
	s_waitcnt lgkmcnt(0)
	v_cndmask_b32_e64 v98, v140, v188, s[36:37]
	s_waitcnt lgkmcnt(0)
	v_cndmask_b32_e64 v99, v141, v189, s[36:37]
	s_waitcnt lgkmcnt(0)
	v_cndmask_b32_e64 v100, v190, v145, s[38:39]
	s_waitcnt lgkmcnt(0)
	v_cndmask_b32_e64 v101, v191, v146, s[38:39]
	v_pk_fma_f32 v[62:63], v[80:81], v[98:99], v[62:63]
	s_mov_b32 s24, 0x3d372713
	v_pk_fma_f32 v[62:63], v[84:85], v[100:101], v[62:63]
	s_mov_b32 s62, 0xc0135761
	v_pk_mul_f32 v[98:99], v[62:63], v[62:63]
	v_pk_mul_f32 v[58:59], v[58:59], v[184:185]
	v_pk_mul_f32 v[98:99], v[62:63], v[98:99]
	s_movk_i32 s15, 0x1600
	v_pk_fma_f32 v[98:99], v[98:99], s[24:25], v[62:63] op_sel_hi:[1,0,1]
	s_nop 0
	v_pk_mul_f32 v[98:99], v[98:99], s[62:63] op_sel_hi:[1,0]
	s_nop 0
	v_exp_f32_e32 v98, v98
	v_exp_f32_e32 v99, v99
	s_nop 0
	v_pk_add_f32 v[98:99], v[98:99], 1.0 op_sel_hi:[1,0]
	s_nop 0
	v_rcp_f32_e32 v98, v98
	v_rcp_f32_e32 v99, v99
	s_nop 0
	v_pk_mul_f32 v[62:63], v[62:63], v[98:99]
	s_nop 0
	v_pk_mul_f32 v[60:61], v[60:61], v[62:63]
	v_cndmask_b32_e64 v62, v136, v147, s[36:37]
	v_cndmask_b32_e64 v63, v137, v174, s[36:37]
	v_cndmask_b32_e64 v98, v186, v138, s[38:39]
	v_cndmask_b32_e64 v99, v187, v139, s[38:39]
	v_pk_fma_f32 v[62:63], v[78:79], v[62:63], v[64:65]
	v_cvt_pk_bf16_f32 v61, v60, v61
	v_pk_fma_f32 v[62:63], v[82:83], v[98:99], v[62:63]
	s_nop 0
	v_pk_mul_f32 v[64:65], v[62:63], v[62:63]
	s_nop 0
	v_pk_mul_f32 v[64:65], v[62:63], v[64:65]
	s_nop 0
	v_pk_fma_f32 v[64:65], v[64:65], s[24:25], v[62:63] op_sel_hi:[1,0,1]
	s_nop 0
	v_pk_mul_f32 v[64:65], v[64:65], s[62:63] op_sel_hi:[1,0]
	s_nop 0
	v_exp_f32_e32 v64, v64
	v_exp_f32_e32 v65, v65
	s_nop 0
	v_pk_add_f32 v[64:65], v[64:65], 1.0 op_sel_hi:[1,0]
	s_nop 0
	v_rcp_f32_e32 v64, v64
	v_rcp_f32_e32 v65, v65
	s_nop 0
	v_pk_mul_f32 v[62:63], v[62:63], v[64:65]
	s_nop 0
	v_pk_mul_f32 v[58:59], v[58:59], v[62:63]
	s_nop 0
	v_cvt_pk_bf16_f32 v60, v58, v59
	v_mov_b64_e32 v[58:59], s[76:77]
	v_mad_i64_i32 v[58:59], s[62:63], v142, s15, v[58:59]
	v_lshl_add_u64 v[58:59], v[162:163], 1, v[58:59]
	global_store_dwordx2 v[58:59], v[60:61], off offset:8
	s_or_b64 exec, exec, s[12:13]
	s_and_saveexec_b64 s[12:13], s[44:45]
	s_cbranch_execnz .LBB0_454

;     __device__ __forceinline__ void operator()(f32x4 (&acc)[2][2][4][2], const Unit& u, int wr, int wc, int fr, int fq) const {
;     ...
;                 const f32x4 w0v = *(const f32x4*)(cw + colg + 4 * n), w1v = *(const f32x4*)(cw + FFN + colg + 4 * n), w2v = *(const f32x4*)(cw + 2 * FFN + colg + 4 * n), cbv = *(const f32x4*)(cb + colg + 4 * n);
;                 f32x4 res[4];
; #pragma unroll
;                 for (int p = 0; p < 2; ++p) {
;                     const f32x2 w0 = {w0v[2 * p], w0v[2 * p + 1]}, w1 = {w1v[2 * p], w1v[2 * p + 1]}, w2 = {w2v[2 * p], w2v[2 * p + 1]}, bb = {cbv[2 * p], cbv[2 * p + 1]};
;                     f32x2 c[4], ps[4], ns[4];
; #pragma unroll
;                     for (int m = 0; m < 4; ++m) { c[m] = (f32x2){acc[ai][0][m][n][2 * p], acc[ai][0][m][n][2 * p + 1]};
;                         ps[m] = (f32x2){__shfl(c[m].x, lprev), __shfl(c[m].y, lprev)}; ns[m] = (f32x2){__shfl(c[m].x, lnext), __shfl(c[m].y, lnext)}; }
;                     f32x2 pe = {0.f, 0.f}, ne = {0.f, 0.f};
;                     if (blk > 0) pe = (f32x2){edgeL[(blk - 1) * 128 + colw + 4 * n + 2 * p], edgeL[(blk - 1) * 128 + colw + 4 * n + 2 * p + 1]};
;                     if (blk < 3) ne = (f32x2){edgeF[(blk + 1) * 128 + colw + 4 * n + 2 * p], edgeF[(blk + 1) * 128 + colw + 4 * n + 2 * p + 1]};
; #pragma unroll
;                     for (int m = 0; m < 4; ++m) {
;                         const f32x2 pvm = f0 ? (m == 0 ? pe : ps[m == 0 ? 0 : m - 1]) : ps[m];
;                         const f32x2 nvm = f15 ? (m == 3 ? ne : ns[m == 3 ? 3 : m + 1]) : ns[m];
;                         f32x2 cu = w1 * c[m] + bb; cu = w0 * pvm + cu; cu = w2 * nvm + cu;
;                         f32x2 tq = (cu * cu) * cu; tq = tq * 0.044715f + cu;
;                         const f32x2 ea = tq * (-2.3022082f);
;                         f32x2 dn; dn.x = __builtin_amdgcn_exp2f(ea.x); dn.y = __builtin_amdgcn_exp2f(ea.y); dn = dn + 1.0f;
;                         f32x2 rc; rc.x = __builtin_amdgcn_rcpf(dn.x); rc.y = __builtin_amdgcn_rcpf(dn.y);
;                         const f32x2 vv = {acc[ai][1][m][n][2 * p], acc[ai][1][m][n][2 * p + 1]};
;                         const f32x2 o = (cu * rc) * vv;
;                         res[m][2 * p] = o.x; res[m][2 * p + 1] = o.y; }
;                 }
; #pragma unroll
.LBB0_458:
	v_mov_b32_e32 v54, v176
	v_mov_b32_e32 v55, v176
	v_pk_mul_f32 v[52:53], v[52:53], v[54:55]
	s_waitcnt vmcnt(0)
	v_pk_fma_f32 v[54:55], v[116:117], v[88:89], v[96:97]
	s_waitcnt lgkmcnt(0)
	v_cndmask_b32_e64 v59, v135, v131, s[36:37]
	v_cndmask_b32_e64 v58, v133, v130, s[36:37]
	s_waitcnt lgkmcnt(0)
	v_cndmask_b32_e64 v61, v134, v69, s[38:39]
	v_cndmask_b32_e64 v60, v132, v68, s[38:39]
	v_pk_fma_f32 v[54:55], v[80:81], v[58:59], v[54:55]
	s_mov_b32 s24, 0x3d372713
	v_pk_fma_f32 v[54:55], v[84:85], v[60:61], v[54:55]
	s_mov_b32 s62, 0xc0135761
	v_pk_mul_f32 v[58:59], v[54:55], v[54:55]
	v_pk_fma_f32 v[56:57], v[114:115], v[86:87], v[94:95]
	v_pk_mul_f32 v[58:59], v[54:55], v[58:59]
	v_pk_mul_f32 v[50:51], v[50:51], v[176:177]
	v_pk_fma_f32 v[58:59], v[58:59], s[24:25], v[54:55] op_sel_hi:[1,0,1]
	s_movk_i32 s15, 0x1600
	v_pk_mul_f32 v[58:59], v[58:59], s[62:63] op_sel_hi:[1,0]
	s_nop 0
	v_exp_f32_e32 v58, v58
	v_exp_f32_e32 v59, v59
	s_nop 0
	v_pk_add_f32 v[58:59], v[58:59], 1.0 op_sel_hi:[1,0]
	s_nop 0
	v_rcp_f32_e32 v58, v58
	v_rcp_f32_e32 v59, v59
	s_nop 0
	v_pk_mul_f32 v[54:55], v[54:55], v[58:59]
	s_nop 0
	v_pk_mul_f32 v[52:53], v[52:53], v[54:55]
	v_cndmask_b32_e64 v55, v129, v121, s[36:37]
	v_cndmask_b32_e64 v54, v127, v120, s[36:37]
	v_cndmask_b32_e64 v59, v128, v67, s[38:39]
	v_cndmask_b32_e64 v58, v126, v66, s[38:39]
	v_pk_fma_f32 v[54:55], v[78:79], v[54:55], v[56:57]
	v_cvt_pk_bf16_f32 v53, v52, v53
	v_pk_fma_f32 v[54:55], v[82:83], v[58:59], v[54:55]
	s_nop 0
	v_pk_mul_f32 v[56:57], v[54:55], v[54:55]
	s_nop 0
	v_pk_mul_f32 v[56:57], v[54:55], v[56:57]
	s_nop 0
	v_pk_fma_f32 v[56:57], v[56:57], s[24:25], v[54:55] op_sel_hi:[1,0,1]
	s_nop 0
	v_pk_mul_f32 v[56:57], v[56:57], s[62:63] op_sel_hi:[1,0]
	s_nop 0
	v_exp_f32_e32 v56, v56
	v_exp_f32_e32 v57, v57
	s_nop 0
	v_pk_add_f32 v[56:57], v[56:57], 1.0 op_sel_hi:[1,0]
	s_nop 0
	v_rcp_f32_e32 v56, v56
	v_rcp_f32_e32 v57, v57
	s_nop 0
	v_pk_mul_f32 v[54:55], v[54:55], v[56:57]
	s_nop 0
	v_pk_mul_f32 v[50:51], v[50:51], v[54:55]
	s_nop 0
	v_cvt_pk_bf16_f32 v52, v50, v51
	v_mov_b64_e32 v[50:51], s[76:77]
	v_mad_i64_i32 v[50:51], s[62:63], v144, s15, v[50:51]
	v_lshl_add_u64 v[50:51], v[162:163], 1, v[50:51]
	global_store_dwordx2 v[50:51], v[52:53], off offset:8
.LBB0_459:
	s_or_b64 exec, exec, s[12:13]
	global_load_dwordx4 v[50:53], v[166:167], off
	global_load_dwordx4 v[58:61], v[178:179], off
	global_load_dwordx4 v[54:57], v[180:181], off
	global_load_dwordx4 v[62:65], v[168:169], off
	s_waitcnt lgkmcnt(0)
	v_mul_f32_e32 v66, 0x4b800000, v172
	v_cndmask_b32_e64 v66, v172, v66, s[58:59]
	v_rsq_f32_e32 v66, v66
	v_mul_f32_e32 v67, 0x4b800000, v175
	v_cndmask_b32_e64 v67, v175, v67, s[60:61]
	v_rsq_f32_e32 v67, v67
	s_waitcnt lgkmcnt(0)
	v_mul_f32_e32 v68, 0x45800000, v66
	v_cndmask_b32_e64 v66, v66, v68, s[58:59]
	v_mov_b32_dpp v115, v111 row_ror:1 row_mask:0xf bank_mask:0xf
	v_pk_mul_f32 v[70:71], v[46:47], v[66:67] op_sel_hi:[1,0]
	v_mul_f32_e32 v46, 0x45800000, v67
	v_cndmask_b32_e64 v46, v67, v46, s[60:61]
	v_pk_mul_f32 v[68:69], v[42:43], v[46:47] op_sel_hi:[1,0]
	v_mov_b32_dpp v47, v110 row_ror:1 row_mask:0xf bank_mask:0xf
	v_mov_b32_dpp v67, v110 row_ror:15 row_mask:0xf bank_mask:0xf
	v_mov_b32_dpp v122, v111 row_ror:15 row_mask:0xf bank_mask:0xf
	v_mov_b32_dpp v99, v70 row_ror:1 row_mask:0xf bank_mask:0xf
	v_mov_b32_dpp v100, v71 row_ror:1 row_mask:0xf bank_mask:0xf
	v_mov_b32_dpp v116, v70 row_ror:15 row_mask:0xf bank_mask:0xf
	v_mov_b32_dpp v117, v71 row_ror:15 row_mask:0xf bank_mask:0xf
	s_waitcnt vmcnt(5)
	v_mov_b32_dpp v83, v68 row_ror:1 row_mask:0xf bank_mask:0xf
	v_mov_b32_dpp v84, v69 row_ror:1 row_mask:0xf bank_mask:0xf
	v_mov_b32_dpp v101, v68 row_ror:15 row_mask:0xf bank_mask:0xf
	v_mov_b32_dpp v102, v69 row_ror:15 row_mask:0xf bank_mask:0xf
	v_mov_b32_dpp v86, v106 row_ror:1 row_mask:0xf bank_mask:0xf
	v_mov_b32_dpp v88, v107 row_ror:1 row_mask:0xf bank_mask:0xf
	v_mov_b32_dpp v85, v106 row_ror:15 row_mask:0xf bank_mask:0xf
	v_mov_b32_dpp v87, v107 row_ror:15 row_mask:0xf bank_mask:0xf
	v_cndmask_b32_e64 v43, 0, 1, s[86:87]
	v_mov_b32_e32 v42, 0
	v_cmp_ne_u32_e64 s[58:59], 1, v43
	s_andn2_b64 vcc, exec, s[86:87]
	v_mov_b32_e32 v78, 0
	v_mov_b32_e32 v79, 0
	s_cbranch_vccnz .LBB0_461
	ds_read_b64 v[78:79], v220

;     __device__ __forceinline__ void operator()(f32x4 (&acc)[2][2][4][2], const Unit& u, int wr, int wc, int fr, int fq) const {
;     ...
;                 const f32x4 w0v = *(const f32x4*)(cw + colg + 4 * n), w1v = *(const f32x4*)(cw + FFN + colg + 4 * n), w2v = *(const f32x4*)(cw + 2 * FFN + colg + 4 * n), cbv = *(const f32x4*)(cb + colg + 4 * n);
;                 f32x4 res[4];
; #pragma unroll
;                 for (int p = 0; p < 2; ++p) {
;                     const f32x2 w0 = {w0v[2 * p], w0v[2 * p + 1]}, w1 = {w1v[2 * p], w1v[2 * p + 1]}, w2 = {w2v[2 * p], w2v[2 * p + 1]}, bb = {cbv[2 * p], cbv[2 * p + 1]};
;                     f32x2 c[4], ps[4], ns[4];
; #pragma unroll
;                     for (int m = 0; m < 4; ++m) { c[m] = (f32x2){acc[ai][0][m][n][2 * p], acc[ai][0][m][n][2 * p + 1]};
;                         ps[m] = (f32x2){__shfl(c[m].x, lprev), __shfl(c[m].y, lprev)}; ns[m] = (f32x2){__shfl(c[m].x, lnext), __shfl(c[m].y, lnext)}; }
;                     f32x2 pe = {0.f, 0.f}, ne = {0.f, 0.f};
;                     if (blk > 0) pe = (f32x2){edgeL[(blk - 1) * 128 + colw + 4 * n + 2 * p], edgeL[(blk - 1) * 128 + colw + 4 * n + 2 * p + 1]};
;                     if (blk < 3) ne = (f32x2){edgeF[(blk + 1) * 128 + colw + 4 * n + 2 * p], edgeF[(blk + 1) * 128 + colw + 4 * n + 2 * p + 1]};
.LBB0_463:
	s_waitcnt lgkmcnt(0)
	v_pk_mul_f32 v[72:73], v[48:49], v[66:67] op_sel_hi:[1,0]
	v_pk_mul_f32 v[48:49], v[44:45], v[46:47] op_sel_hi:[1,0]
	v_mov_b32_dpp v118, v112 row_ror:1 row_mask:0xf bank_mask:0xf
	v_mov_b32_dpp v119, v113 row_ror:1 row_mask:0xf bank_mask:0xf
	v_mov_b32_dpp v123, v112 row_ror:15 row_mask:0xf bank_mask:0xf
	v_mov_b32_dpp v124, v113 row_ror:15 row_mask:0xf bank_mask:0xf
	v_mov_b32_dpp v103, v72 row_ror:1 row_mask:0xf bank_mask:0xf
	v_mov_b32_dpp v104, v73 row_ror:1 row_mask:0xf bank_mask:0xf
	v_mov_b32_dpp v120, v72 row_ror:15 row_mask:0xf bank_mask:0xf
	v_mov_b32_dpp v121, v73 row_ror:15 row_mask:0xf bank_mask:0xf
	v_mov_b32_dpp v89, v48 row_ror:1 row_mask:0xf bank_mask:0xf
	s_waitcnt vmcnt(4)
	v_mov_b32_dpp v94, v49 row_ror:1 row_mask:0xf bank_mask:0xf
	v_mov_b32_dpp v105, v48 row_ror:15 row_mask:0xf bank_mask:0xf
	v_mov_b32_dpp v114, v49 row_ror:15 row_mask:0xf bank_mask:0xf
	v_mov_b32_dpp v96, v108 row_ror:1 row_mask:0xf bank_mask:0xf
	v_mov_b32_dpp v98, v109 row_ror:1 row_mask:0xf bank_mask:0xf
	v_mov_b32_dpp v95, v108 row_ror:15 row_mask:0xf bank_mask:0xf
	v_mov_b32_dpp v97, v109 row_ror:15 row_mask:0xf bank_mask:0xf
	v_mov_b32_e32 v44, 0
	s_and_b64 vcc, exec, s[58:59]
	v_mov_b32_e32 v80, 0
	v_mov_b32_e32 v81, 0
	s_cbranch_vccnz .LBB0_466
	ds_read_b64 v[80:81], v220 offset:8
	s_and_b64 vcc, exec, s[60:61]
	v_mov_b32_e32 v45, 0
	s_cbranch_vccnz .LBB0_467

; __device__ __forceinline__ unsigned cvt_pk_bf16(float lo, float hi) { return pk2(lo, hi); }
;     __device__ __forceinline__ void operator()(f32x4 (&acc)[2][2][4][2], const Unit& u, int wr, int wc, int fr, int fq) const {
;     ...
;                     for (int m = 0; m < 4; ++m) { c[m] = (f32x2){acc[ai][0][m][n][2 * p], acc[ai][0][m][n][2 * p + 1]};
;                         ps[m] = (f32x2){__shfl(c[m].x, lprev), __shfl(c[m].y, lprev)}; ns[m] = (f32x2){__shfl(c[m].x, lnext), __shfl(c[m].y, lnext)}; }
;                     f32x2 pe = {0.f, 0.f}, ne = {0.f, 0.f};
;                     if (blk > 0) pe = (f32x2){edgeL[(blk - 1) * 128 + colw + 4 * n + 2 * p], edgeL[(blk - 1) * 128 + colw + 4 * n + 2 * p + 1]};
;                     if (blk < 3) ne = (f32x2){edgeF[(blk + 1) * 128 + colw + 4 * n + 2 * p], edgeF[(blk + 1) * 128 + colw + 4 * n + 2 * p + 1]};
; #pragma unroll
;                     for (int m = 0; m < 4; ++m) {
;                         const f32x2 pvm = f0 ? (m == 0 ? pe : ps[m == 0 ? 0 : m - 1]) : ps[m];
;                         const f32x2 nvm = f15 ? (m == 3 ? ne : ns[m == 3 ? 3 : m + 1]) : ns[m];
;                         f32x2 cu = w1 * c[m] + bb; cu = w0 * pvm + cu; cu = w2 * nvm + cu;
;                         f32x2 tq = (cu * cu) * cu; tq = tq * 0.044715f + cu;
;                         const f32x2 ea = tq * (-2.3022082f);
;                         f32x2 dn; dn.x = __builtin_amdgcn_exp2f(ea.x); dn.y = __builtin_amdgcn_exp2f(ea.y); dn = dn + 1.0f;
;                         f32x2 rc; rc.x = __builtin_amdgcn_rcpf(dn.x); rc.y = __builtin_amdgcn_rcpf(dn.y);
;                         const f32x2 vv = {acc[ai][1][m][n][2 * p], acc[ai][1][m][n][2 * p + 1]};
;                         const f32x2 o = (cu * rc) * vv;
;                         res[m][2 * p] = o.x; res[m][2 * p + 1] = o.y; }
;                 }
; #pragma unroll
;                 for (int m = 0; m < 4; ++m) { const int j = ai * 128 + wr * 64 + m * 16 + fr;
;                     u32x2 w; w.x = cvt_pk_bf16(res[m][0], res[m][1]); w.y = cvt_pk_bf16(res[m][2], res[m][3]);
;                     if (j >= 1 && j <= 254) *(u32x2*)(act + (size_t)(rowt + j) * FFN + colg + 4 * n) = w; }
.LBB0_468:
	v_mov_b32_e32 v126, v164
	v_mov_b32_e32 v127, v164
	s_waitcnt lgkmcnt(0)
	v_cndmask_b32_e64 v79, v115, v79, s[36:37]
	v_cndmask_b32_e64 v78, v47, v78, s[36:37]
	s_waitcnt vmcnt(0)
	v_pk_fma_f32 v[110:111], v[110:111], v[58:59], v[62:63]
	v_pk_mul_f32 v[40:41], v[40:41], v[126:127]
	v_cndmask_b32_e64 v127, v122, v117, s[38:39]
	v_cndmask_b32_e64 v126, v67, v116, s[38:39]
	v_pk_fma_f32 v[78:79], v[50:51], v[78:79], v[110:111]
	s_mov_b32 s24, 0x3d372713
	v_pk_fma_f32 v[78:79], v[54:55], v[126:127], v[78:79]
	s_mov_b32 s62, 0xc0135761
	v_pk_mul_f32 v[110:111], v[78:79], v[78:79]
	v_pk_mul_f32 v[38:39], v[38:39], v[164:165]
	v_pk_mul_f32 v[110:111], v[78:79], v[110:111]
	v_pk_fma_f32 v[112:113], v[112:113], v[60:61], v[64:65]
	v_pk_fma_f32 v[110:111], v[110:111], s[24:25], v[78:79] op_sel_hi:[1,0,1]
	s_movk_i32 s15, 0x1600
	v_pk_mul_f32 v[110:111], v[110:111], s[62:63] op_sel_hi:[1,0]
	s_nop 0
	v_exp_f32_e32 v110, v110
	v_exp_f32_e32 v111, v111
	s_nop 0
	v_pk_add_f32 v[110:111], v[110:111], 1.0 op_sel_hi:[1,0]
	s_nop 0
	v_rcp_f32_e32 v110, v110
	v_rcp_f32_e32 v111, v111
	s_nop 0
	v_pk_mul_f32 v[78:79], v[78:79], v[110:111]
	s_nop 0
	v_pk_mul_f32 v[38:39], v[38:39], v[78:79]
	s_waitcnt lgkmcnt(0)
	v_cndmask_b32_e64 v79, v119, v81, s[36:37]
	v_cndmask_b32_e64 v78, v118, v80, s[36:37]
	v_pk_fma_f32 v[78:79], v[52:53], v[78:79], v[112:113]
	v_cndmask_b32_e64 v81, v124, v121, s[38:39]
	v_cndmask_b32_e64 v80, v123, v120, s[38:39]
	v_pk_fma_f32 v[78:79], v[56:57], v[80:81], v[78:79]
	s_nop 0
	v_pk_mul_f32 v[80:81], v[78:79], v[78:79]
	s_nop 0
	v_pk_mul_f32 v[80:81], v[78:79], v[80:81]
	s_nop 0
	v_pk_fma_f32 v[80:81], v[80:81], s[24:25], v[78:79] op_sel_hi:[1,0,1]
	s_nop 0
	v_pk_mul_f32 v[80:81], v[80:81], s[62:63] op_sel_hi:[1,0]
	s_nop 0
	v_exp_f32_e32 v80, v80
	v_exp_f32_e32 v81, v81
	s_nop 0
	v_pk_add_f32 v[80:81], v[80:81], 1.0 op_sel_hi:[1,0]
	s_nop 0
	v_rcp_f32_e32 v80, v80
	v_rcp_f32_e32 v81, v81
	s_nop 0
	v_pk_mul_f32 v[78:79], v[78:79], v[80:81]
	s_nop 0
	v_pk_mul_f32 v[40:41], v[40:41], v[78:79]
	s_nop 0
	v_cvt_pk_bf16_f32 v41, v40, v41
	v_cvt_pk_bf16_f32 v40, v38, v39
	v_mov_b64_e32 v[38:39], s[76:77]
	v_mad_i64_i32 v[38:39], s[62:63], v82, s15, v[38:39]
	v_lshl_add_u64 v[38:39], v[162:163], 1, v[38:39]
	global_store_dwordx2 v[38:39], v[40:41], off
.LBB0_469:
	s_or_b64 exec, exec, s[12:13]
	v_mov_b32_e32 v67, v66
	s_waitcnt lgkmcnt(0)
	v_add_u32_e32 v78, s2, v214
	s_and_saveexec_b64 s[12:13], s[50:51]
	s_cbranch_execz .LBB0_471
	v_mov_b32_e32 v38, v66
	v_mov_b32_e32 v39, v66
	v_pk_mul_f32 v[36:37], v[36:37], v[38:39]
	s_waitcnt vmcnt(0)
	v_pk_fma_f32 v[38:39], v[72:73], v[60:61], v[64:65]
	v_pk_fma_f32 v[40:41], v[70:71], v[58:59], v[62:63]
	s_waitcnt lgkmcnt(0)
	v_cndmask_b32_e64 v70, v103, v118, s[36:37]
	s_waitcnt lgkmcnt(0)
	v_cndmask_b32_e64 v71, v104, v119, s[36:37]
	s_waitcnt lgkmcnt(0)
	v_cndmask_b32_e64 v72, v120, v105, s[38:39]
	s_waitcnt lgkmcnt(0)
	v_cndmask_b32_e64 v73, v121, v114, s[38:39]
	v_pk_fma_f32 v[38:39], v[52:53], v[70:71], v[38:39]
	s_mov_b32 s24, 0x3d372713
	v_pk_fma_f32 v[38:39], v[56:57], v[72:73], v[38:39]
	s_mov_b32 s62, 0xc0135761
	v_pk_mul_f32 v[70:71], v[38:39], v[38:39]
	v_pk_mul_f32 v[34:35], v[34:35], v[66:67]
	v_pk_mul_f32 v[70:71], v[38:39], v[70:71]
	s_movk_i32 s15, 0x1600
	v_pk_fma_f32 v[70:71], v[70:71], s[24:25], v[38:39] op_sel_hi:[1,0,1]
	s_nop 0
	v_pk_mul_f32 v[70:71], v[70:71], s[62:63] op_sel_hi:[1,0]
	s_nop 0
	v_exp_f32_e32 v70, v70
	v_exp_f32_e32 v71, v71
	s_nop 0
	v_pk_add_f32 v[70:71], v[70:71], 1.0 op_sel_hi:[1,0]
	s_nop 0
	v_rcp_f32_e32 v70, v70
	v_rcp_f32_e32 v71, v71
	s_nop 0
	v_pk_mul_f32 v[38:39], v[38:39], v[70:71]
	s_nop 0
	v_pk_mul_f32 v[36:37], v[36:37], v[38:39]
	v_cndmask_b32_e64 v38, v99, v47, s[36:37]
	v_cndmask_b32_e64 v39, v100, v115, s[36:37]
	v_cndmask_b32_e64 v70, v116, v101, s[38:39]
	v_cndmask_b32_e64 v71, v117, v102, s[38:39]
	v_pk_fma_f32 v[38:39], v[50:51], v[38:39], v[40:41]
	v_cvt_pk_bf16_f32 v37, v36, v37
	v_pk_fma_f32 v[38:39], v[54:55], v[70:71], v[38:39]
	s_nop 0
	v_pk_mul_f32 v[40:41], v[38:39], v[38:39]
	s_nop 0
	v_pk_mul_f32 v[40:41], v[38:39], v[40:41]
	s_nop 0
	v_pk_fma_f32 v[40:41], v[40:41], s[24:25], v[38:39] op_sel_hi:[1,0,1]
	s_nop 0
	v_pk_mul_f32 v[40:41], v[40:41], s[62:63] op_sel_hi:[1,0]
	s_nop 0
	v_exp_f32_e32 v40, v40
	v_exp_f32_e32 v41, v41
	s_nop 0
	v_pk_add_f32 v[40:41], v[40:41], 1.0 op_sel_hi:[1,0]
	s_nop 0
	v_rcp_f32_e32 v40, v40
	v_rcp_f32_e32 v41, v41
	s_nop 0
	v_pk_mul_f32 v[38:39], v[38:39], v[40:41]
	s_nop 0
	v_pk_mul_f32 v[34:35], v[34:35], v[38:39]
	s_nop 0
	v_cvt_pk_bf16_f32 v36, v34, v35
	v_mov_b64_e32 v[34:35], s[76:77]
	v_mad_i64_i32 v[34:35], s[62:63], v78, s15, v[34:35]
	v_lshl_add_u64 v[34:35], v[162:163], 1, v[34:35]
	global_store_dwordx2 v[34:35], v[36:37], off
;     __device__ __forceinline__ void operator()(f32x4 (&acc)[2][2][4][2], const Unit& u, int wr, int wc, int fr, int fq) const {
;     ...
;                 const f32x4 w0v = *(const f32x4*)(cw + colg + 4 * n), w1v = *(const f32x4*)(cw + FFN + colg + 4 * n), w2v = *(const f32x4*)(cw + 2 * FFN + colg + 4 * n), cbv = *(const f32x4*)(cb + colg + 4 * n);
;                 f32x4 res[4];
; #pragma unroll
;                 for (int p = 0; p < 2; ++p) {
;                     const f32x2 w0 = {w0v[2 * p], w0v[2 * p + 1]}, w1 = {w1v[2 * p], w1v[2 * p + 1]}, w2 = {w2v[2 * p], w2v[2 * p + 1]}, bb = {cbv[2 * p], cbv[2 * p + 1]};
;                     f32x2 c[4], ps[4], ns[4];
; #pragma unroll
;                     for (int m = 0; m < 4; ++m) { c[m] = (f32x2){acc[ai][0][m][n][2 * p], acc[ai][0][m][n][2 * p + 1]};
;                         ps[m] = (f32x2){__shfl(c[m].x, lprev), __shfl(c[m].y, lprev)}; ns[m] = (f32x2){__shfl(c[m].x, lnext), __shfl(c[m].y, lnext)}; }
;                     f32x2 pe = {0.f, 0.f}, ne = {0.f, 0.f};
;                     if (blk > 0) pe = (f32x2){edgeL[(blk - 1) * 128 + colw + 4 * n + 2 * p], edgeL[(blk - 1) * 128 + colw + 4 * n + 2 * p + 1]};
;                     if (blk < 3) ne = (f32x2){edgeF[(blk + 1) * 128 + colw + 4 * n + 2 * p], edgeF[(blk + 1) * 128 + colw + 4 * n + 2 * p + 1]};
; #pragma unroll
;                     for (int m = 0; m < 4; ++m) {
;                         const f32x2 pvm = f0 ? (m == 0 ? pe : ps[m == 0 ? 0 : m - 1]) : ps[m];
;                         const f32x2 nvm = f15 ? (m == 3 ? ne : ns[m == 3 ? 3 : m + 1]) : ns[m];
;                         f32x2 cu = w1 * c[m] + bb; cu = w0 * pvm + cu; cu = w2 * nvm + cu;
;                         f32x2 tq = (cu * cu) * cu; tq = tq * 0.044715f + cu;
;                         const f32x2 ea = tq * (-2.3022082f);
;                         f32x2 dn; dn.x = __builtin_amdgcn_exp2f(ea.x); dn.y = __builtin_amdgcn_exp2f(ea.y); dn = dn + 1.0f;
;                         f32x2 rc; rc.x = __builtin_amdgcn_rcpf(dn.x); rc.y = __builtin_amdgcn_rcpf(dn.y);
;                         const f32x2 vv = {acc[ai][1][m][n][2 * p], acc[ai][1][m][n][2 * p + 1]};
;                         const f32x2 o = (cu * rc) * vv;
;                         res[m][2 * p] = o.x; res[m][2 * p + 1] = o.y; }
;                 }
; #pragma unroll
.LBB0_471:
	s_or_b64 exec, exec, s[12:13]
	v_mov_b32_e32 v47, v46
	v_add_u32_e32 v70, s2, v215
	s_and_saveexec_b64 s[12:13], s[52:53]
	s_cbranch_execz .LBB0_473
	v_mov_b32_e32 v34, v46
	v_mov_b32_e32 v35, v46
	v_pk_mul_f32 v[32:33], v[32:33], v[34:35]
	s_waitcnt vmcnt(0)
	v_pk_fma_f32 v[34:35], v[48:49], v[60:61], v[64:65]
	s_waitcnt lgkmcnt(0)
	v_cndmask_b32_e64 v38, v89, v103, s[36:37]
	s_waitcnt lgkmcnt(0)
	v_cndmask_b32_e64 v39, v94, v104, s[36:37]
	s_waitcnt lgkmcnt(0)
	v_cndmask_b32_e64 v40, v105, v95, s[38:39]
	s_waitcnt lgkmcnt(0)
	v_cndmask_b32_e64 v41, v114, v97, s[38:39]
	v_pk_fma_f32 v[34:35], v[52:53], v[38:39], v[34:35]
	s_mov_b32 s24, 0x3d372713
	v_pk_fma_f32 v[34:35], v[56:57], v[40:41], v[34:35]
	s_mov_b32 s62, 0xc0135761
	v_pk_mul_f32 v[38:39], v[34:35], v[34:35]
	v_pk_fma_f32 v[36:37], v[68:69], v[58:59], v[62:63]
	v_pk_mul_f32 v[38:39], v[34:35], v[38:39]
	v_pk_mul_f32 v[30:31], v[30:31], v[46:47]
	v_pk_fma_f32 v[38:39], v[38:39], s[24:25], v[34:35] op_sel_hi:[1,0,1]
	s_movk_i32 s15, 0x1600
	v_pk_mul_f32 v[38:39], v[38:39], s[62:63] op_sel_hi:[1,0]
	s_nop 0
	v_exp_f32_e32 v38, v38
	v_exp_f32_e32 v39, v39
	s_nop 0
	v_pk_add_f32 v[38:39], v[38:39], 1.0 op_sel_hi:[1,0]
	s_nop 0
	v_rcp_f32_e32 v38, v38
	v_rcp_f32_e32 v39, v39
	s_nop 0
	v_pk_mul_f32 v[34:35], v[34:35], v[38:39]
	s_nop 0
	v_pk_mul_f32 v[32:33], v[32:33], v[34:35]
	v_cndmask_b32_e64 v34, v83, v99, s[36:37]
	v_cndmask_b32_e64 v35, v84, v100, s[36:37]
	v_cndmask_b32_e64 v38, v101, v85, s[38:39]
	v_cndmask_b32_e64 v39, v102, v87, s[38:39]
	v_pk_fma_f32 v[34:35], v[50:51], v[34:35], v[36:37]
	v_cvt_pk_bf16_f32 v33, v32, v33
	v_pk_fma_f32 v[34:35], v[54:55], v[38:39], v[34:35]
	s_nop 0
	v_pk_mul_f32 v[36:37], v[34:35], v[34:35]
	s_nop 0
	v_pk_mul_f32 v[36:37], v[34:35], v[36:37]
	s_nop 0
	v_pk_fma_f32 v[36:37], v[36:37], s[24:25], v[34:35] op_sel_hi:[1,0,1]
	s_nop 0
	v_pk_mul_f32 v[36:37], v[36:37], s[62:63] op_sel_hi:[1,0]
	s_nop 0
	v_exp_f32_e32 v36, v36
	v_exp_f32_e32 v37, v37
	s_nop 0
	v_pk_add_f32 v[36:37], v[36:37], 1.0 op_sel_hi:[1,0]
	s_nop 0
	v_rcp_f32_e32 v36, v36
	v_rcp_f32_e32 v37, v37
	s_nop 0
	v_pk_mul_f32 v[34:35], v[34:35], v[36:37]
	s_nop 0
	v_pk_mul_f32 v[30:31], v[30:31], v[34:35]
	s_nop 0
	v_cvt_pk_bf16_f32 v32, v30, v31
	v_mov_b64_e32 v[30:31], s[76:77]
	v_mad_i64_i32 v[30:31], s[62:63], v70, s15, v[30:31]
	v_lshl_add_u64 v[30:31], v[162:163], 1, v[30:31]
	global_store_dwordx2 v[30:31], v[32:33], off
.LBB0_473:
	s_or_b64 exec, exec, s[12:13]
	v_add_u32_e32 v68, s2, v216
	s_and_saveexec_b64 s[12:13], s[54:55]
	s_cbranch_execz .LBB0_475
	v_mov_b32_e32 v30, v160
	v_mov_b32_e32 v31, v160
	v_pk_mul_f32 v[28:29], v[28:29], v[30:31]
	s_waitcnt vmcnt(0)
	v_pk_fma_f32 v[30:31], v[108:109], v[60:61], v[64:65]
	s_waitcnt lgkmcnt(0)
	v_cndmask_b32_e64 v35, v98, v94, s[36:37]
	v_cndmask_b32_e64 v34, v96, v89, s[36:37]
	s_waitcnt lgkmcnt(0)
	v_cndmask_b32_e64 v37, v97, v45, s[38:39]
	v_cndmask_b32_e64 v36, v95, v44, s[38:39]
	v_pk_fma_f32 v[30:31], v[52:53], v[34:35], v[30:31]
	s_mov_b32 s2, 0x3d372713
	v_pk_fma_f32 v[30:31], v[56:57], v[36:37], v[30:31]
	s_mov_b32 s24, 0xc0135761
	v_pk_mul_f32 v[34:35], v[30:31], v[30:31]
	v_pk_fma_f32 v[32:33], v[106:107], v[58:59], v[62:63]
	v_pk_mul_f32 v[34:35], v[30:31], v[34:35]
	v_pk_mul_f32 v[26:27], v[26:27], v[160:161]
	v_pk_fma_f32 v[34:35], v[34:35], s[2:3], v[30:31] op_sel_hi:[1,0,1]
	s_nop 0
	v_pk_mul_f32 v[34:35], v[34:35], s[24:25] op_sel_hi:[1,0]
	s_nop 0
	v_exp_f32_e32 v34, v34
	v_exp_f32_e32 v35, v35
	s_nop 0
	v_pk_add_f32 v[34:35], v[34:35], 1.0 op_sel_hi:[1,0]
	s_nop 0
	v_rcp_f32_e32 v34, v34
	v_rcp_f32_e32 v35, v35
	s_nop 0
	v_pk_mul_f32 v[30:31], v[30:31], v[34:35]
	s_nop 0
	v_pk_mul_f32 v[28:29], v[28:29], v[30:31]
	v_cndmask_b32_e64 v31, v88, v84, s[36:37]
	v_cndmask_b32_e64 v30, v86, v83, s[36:37]
	v_cndmask_b32_e64 v35, v87, v43, s[38:39]
	v_cndmask_b32_e64 v34, v85, v42, s[38:39]
	v_pk_fma_f32 v[30:31], v[50:51], v[30:31], v[32:33]
	v_cvt_pk_bf16_f32 v29, v28, v29
	v_pk_fma_f32 v[30:31], v[54:55], v[34:35], v[30:31]
	s_nop 0
	v_pk_mul_f32 v[32:33], v[30:31], v[30:31]
	s_nop 0
	v_pk_mul_f32 v[32:33], v[30:31], v[32:33]
	s_nop 0
	v_pk_fma_f32 v[32:33], v[32:33], s[2:3], v[30:31] op_sel_hi:[1,0,1]
	s_movk_i32 s2, 0x1600
	v_pk_mul_f32 v[32:33], v[32:33], s[24:25] op_sel_hi:[1,0]
	s_nop 0
	v_exp_f32_e32 v32, v32
	v_exp_f32_e32 v33, v33
	s_nop 0
	v_pk_add_f32 v[32:33], v[32:33], 1.0 op_sel_hi:[1,0]
	s_nop 0
	v_rcp_f32_e32 v32, v32
	v_rcp_f32_e32 v33, v33
	s_nop 0
	v_pk_mul_f32 v[30:31], v[30:31], v[32:33]
	s_nop 0
	v_pk_mul_f32 v[26:27], v[26:27], v[30:31]
	s_nop 0
	v_cvt_pk_bf16_f32 v28, v26, v27
	v_mov_b64_e32 v[26:27], s[76:77]
	v_mad_i64_i32 v[26:27], s[62:63], v68, s2, v[26:27]
	v_lshl_add_u64 v[26:27], v[162:163], 1, v[26:27]
	global_store_dwordx2 v[26:27], v[28:29], off
.LBB0_475:
	s_or_b64 exec, exec, s[12:13]
	s_mov_b64 s[12:13], 0x2c10
	v_lshl_add_u64 v[30:31], v[166:167], 0, s[12:13]
	s_mov_b64 s[12:13], 0x5810
	v_lshl_add_u64 v[32:33], v[166:167], 0, s[12:13]
	global_load_dwordx4 v[26:29], v[166:167], off offset:16
	global_load_dwordx4 v[34:37], v[30:31], off
	s_nop 0
	global_load_dwordx4 v[30:33], v[32:33], off
	s_nop 0
	global_load_dwordx4 v[38:41], v[168:169], off offset:16
	v_pk_mul_f32 v[42:43], v[22:23], v[66:67]
	v_pk_mul_f32 v[22:23], v[18:19], v[46:47]
	s_waitcnt lgkmcnt(0)
	v_mov_b32_dpp v81, v90 row_ror:1 row_mask:0xf bank_mask:0xf
	v_mov_b32_dpp v83, v91 row_ror:1 row_mask:0xf bank_mask:0xf
	v_mov_b32_dpp v94, v90 row_ror:15 row_mask:0xf bank_mask:0xf
	v_mov_b32_dpp v95, v91 row_ror:15 row_mask:0xf bank_mask:0xf
	s_waitcnt vmcnt(4)
	v_mov_b32_dpp v64, v42 row_ror:1 row_mask:0xf bank_mask:0xf
	v_mov_b32_dpp v65, v43 row_ror:1 row_mask:0xf bank_mask:0xf
	v_mov_b32_dpp v84, v42 row_ror:15 row_mask:0xf bank_mask:0xf
	v_mov_b32_dpp v85, v43 row_ror:15 row_mask:0xf bank_mask:0xf
	v_mov_b32_dpp v52, v22 row_ror:1 row_mask:0xf bank_mask:0xf
	v_mov_b32_dpp v53, v23 row_ror:1 row_mask:0xf bank_mask:0xf
	v_mov_b32_dpp v69, v22 row_ror:15 row_mask:0xf bank_mask:0xf
	v_mov_b32_dpp v71, v23 row_ror:15 row_mask:0xf bank_mask:0xf
	v_mov_b32_dpp v55, v74 row_ror:1 row_mask:0xf bank_mask:0xf
	v_mov_b32_dpp v57, v75 row_ror:1 row_mask:0xf bank_mask:0xf
	v_mov_b32_dpp v54, v74 row_ror:15 row_mask:0xf bank_mask:0xf
	v_mov_b32_dpp v56, v75 row_ror:15 row_mask:0xf bank_mask:0xf
	v_mov_b32_e32 v18, 0
	s_and_b64 vcc, exec, s[58:59]
	v_mov_b32_e32 v48, 0
	v_mov_b32_e32 v49, 0
	s_cbranch_vccnz .LBB0_477
	ds_read_b64 v[48:49], v220 offset:16

;     __device__ __forceinline__ void operator()(f32x4 (&acc)[2][2][4][2], const Unit& u, int wr, int wc, int fr, int fq) const {
;     ...
;                 const f32x4 w0v = *(const f32x4*)(cw + colg + 4 * n), w1v = *(const f32x4*)(cw + FFN + colg + 4 * n), w2v = *(const f32x4*)(cw + 2 * FFN + colg + 4 * n), cbv = *(const f32x4*)(cb + colg + 4 * n);
;                 f32x4 res[4];
; #pragma unroll
;                 for (int p = 0; p < 2; ++p) {
;                     const f32x2 w0 = {w0v[2 * p], w0v[2 * p + 1]}, w1 = {w1v[2 * p], w1v[2 * p + 1]}, w2 = {w2v[2 * p], w2v[2 * p + 1]}, bb = {cbv[2 * p], cbv[2 * p + 1]};
;                     f32x2 c[4], ps[4], ns[4];
; #pragma unroll
;                     for (int m = 0; m < 4; ++m) { c[m] = (f32x2){acc[ai][0][m][n][2 * p], acc[ai][0][m][n][2 * p + 1]};
;                         ps[m] = (f32x2){__shfl(c[m].x, lprev), __shfl(c[m].y, lprev)}; ns[m] = (f32x2){__shfl(c[m].x, lnext), __shfl(c[m].y, lnext)}; }
;                     f32x2 pe = {0.f, 0.f}, ne = {0.f, 0.f};
;                     if (blk > 0) pe = (f32x2){edgeL[(blk - 1) * 128 + colw + 4 * n + 2 * p], edgeL[(blk - 1) * 128 + colw + 4 * n + 2 * p + 1]};
;                     if (blk < 3) ne = (f32x2){edgeF[(blk + 1) * 128 + colw + 4 * n + 2 * p], edgeF[(blk + 1) * 128 + colw + 4 * n + 2 * p + 1]};
.LBB0_479:
	v_mov_b32_e32 v44, v66
	v_mov_b32_e32 v45, v66
	v_pk_mul_f32 v[44:45], v[24:25], v[44:45]
	v_mov_b32_e32 v24, v46
	v_mov_b32_e32 v25, v46
	v_pk_mul_f32 v[24:25], v[20:21], v[24:25]
	v_mov_b32_dpp v86, v92 row_ror:1 row_mask:0xf bank_mask:0xf
	v_mov_b32_dpp v87, v93 row_ror:1 row_mask:0xf bank_mask:0xf
	v_mov_b32_dpp v96, v92 row_ror:15 row_mask:0xf bank_mask:0xf
	v_mov_b32_dpp v97, v93 row_ror:15 row_mask:0xf bank_mask:0xf
	v_mov_b32_dpp v72, v44 row_ror:1 row_mask:0xf bank_mask:0xf
	v_mov_b32_dpp v73, v45 row_ror:1 row_mask:0xf bank_mask:0xf
	v_mov_b32_dpp v88, v44 row_ror:15 row_mask:0xf bank_mask:0xf
	v_mov_b32_dpp v89, v45 row_ror:15 row_mask:0xf bank_mask:0xf
	v_mov_b32_dpp v58, v24 row_ror:1 row_mask:0xf bank_mask:0xf
	v_mov_b32_dpp v59, v25 row_ror:1 row_mask:0xf bank_mask:0xf
	v_mov_b32_dpp v79, v24 row_ror:15 row_mask:0xf bank_mask:0xf
	v_mov_b32_dpp v80, v25 row_ror:15 row_mask:0xf bank_mask:0xf
	v_mov_b32_dpp v61, v76 row_ror:1 row_mask:0xf bank_mask:0xf
	v_mov_b32_dpp v63, v77 row_ror:1 row_mask:0xf bank_mask:0xf
	v_mov_b32_dpp v60, v76 row_ror:15 row_mask:0xf bank_mask:0xf
	v_mov_b32_dpp v62, v77 row_ror:15 row_mask:0xf bank_mask:0xf
	v_mov_b32_e32 v20, 0
	s_and_b64 vcc, exec, s[58:59]
	v_mov_b32_e32 v50, 0
	v_mov_b32_e32 v51, 0
	s_cbranch_vccnz .LBB0_489
	ds_read_b64 v[50:51], v220 offset:24
	s_and_b64 vcc, exec, s[60:61]
	v_mov_b32_e32 v21, 0
	s_cbranch_vccnz .LBB0_490

; __device__ __forceinline__ unsigned cvt_pk_bf16(float lo, float hi) { return pk2(lo, hi); }
;     __device__ __forceinline__ void operator()(f32x4 (&acc)[2][2][4][2], const Unit& u, int wr, int wc, int fr, int fq) const {
;     ...
;                     for (int m = 0; m < 4; ++m) {
;                         const f32x2 pvm = f0 ? (m == 0 ? pe : ps[m == 0 ? 0 : m - 1]) : ps[m];
;                         const f32x2 nvm = f15 ? (m == 3 ? ne : ns[m == 3 ? 3 : m + 1]) : ns[m];
;                         f32x2 cu = w1 * c[m] + bb; cu = w0 * pvm + cu; cu = w2 * nvm + cu;
;                         f32x2 tq = (cu * cu) * cu; tq = tq * 0.044715f + cu;
;                         const f32x2 ea = tq * (-2.3022082f);
;                         f32x2 dn; dn.x = __builtin_amdgcn_exp2f(ea.x); dn.y = __builtin_amdgcn_exp2f(ea.y); dn = dn + 1.0f;
;                         f32x2 rc; rc.x = __builtin_amdgcn_rcpf(dn.x); rc.y = __builtin_amdgcn_rcpf(dn.y);
;                         const f32x2 vv = {acc[ai][1][m][n][2 * p], acc[ai][1][m][n][2 * p + 1]};
;                         const f32x2 o = (cu * rc) * vv;
;                         res[m][2 * p] = o.x; res[m][2 * p + 1] = o.y; }
;                 }
; #pragma unroll
;                 for (int m = 0; m < 4; ++m) { const int j = ai * 128 + wr * 64 + m * 16 + fr;
;                     u32x2 w; w.x = cvt_pk_bf16(res[m][0], res[m][1]); w.y = cvt_pk_bf16(res[m][2], res[m][3]);
;                     if (j >= 1 && j <= 254) *(u32x2*)(act + (size_t)(rowt + j) * FFN + colg + 4 * n) = w; }
.LBB0_483:
	v_mov_b32_e32 v14, v66
	v_mov_b32_e32 v15, v66
	v_pk_mul_f32 v[12:13], v[12:13], v[14:15]
	s_waitcnt vmcnt(0)
	v_pk_fma_f32 v[14:15], v[44:45], v[36:37], v[40:41]
	v_pk_fma_f32 v[16:17], v[42:43], v[34:35], v[38:39]
	s_waitcnt lgkmcnt(0)
	v_cndmask_b32_e64 v42, v72, v86, s[36:37]
	s_waitcnt lgkmcnt(10)
	v_cndmask_b32_e64 v43, v73, v87, s[36:37]
	s_waitcnt lgkmcnt(5)
	v_cndmask_b32_e64 v44, v88, v79, s[38:39]
	s_waitcnt lgkmcnt(4)
	v_cndmask_b32_e64 v45, v89, v80, s[38:39]
	v_pk_fma_f32 v[14:15], v[28:29], v[42:43], v[14:15]
	s_mov_b32 s2, 0x3d372713
	v_pk_fma_f32 v[14:15], v[32:33], v[44:45], v[14:15]
	s_mov_b32 s24, 0xc0135761
	v_pk_mul_f32 v[42:43], v[14:15], v[14:15]
	v_pk_mul_f32 v[10:11], v[10:11], v[66:67]
	v_pk_mul_f32 v[42:43], v[14:15], v[42:43]
	s_nop 0
	v_pk_fma_f32 v[42:43], v[42:43], s[2:3], v[14:15] op_sel_hi:[1,0,1]
	s_nop 0
	v_pk_mul_f32 v[42:43], v[42:43], s[24:25] op_sel_hi:[1,0]
	s_nop 0
	v_exp_f32_e32 v42, v42
	v_exp_f32_e32 v43, v43
	s_nop 0
	v_pk_add_f32 v[42:43], v[42:43], 1.0 op_sel_hi:[1,0]
	s_nop 0
	v_rcp_f32_e32 v42, v42
	v_rcp_f32_e32 v43, v43
	s_nop 0
	v_pk_mul_f32 v[14:15], v[14:15], v[42:43]
	s_nop 0
	v_pk_mul_f32 v[12:13], v[12:13], v[14:15]
	v_cndmask_b32_e64 v14, v64, v81, s[36:37]
	v_cndmask_b32_e64 v15, v65, v83, s[36:37]
	v_cndmask_b32_e64 v42, v84, v69, s[38:39]
	v_cndmask_b32_e64 v43, v85, v71, s[38:39]
	v_pk_fma_f32 v[14:15], v[26:27], v[14:15], v[16:17]
	v_cvt_pk_bf16_f32 v13, v12, v13
	v_pk_fma_f32 v[14:15], v[30:31], v[42:43], v[14:15]
	s_nop 0
	v_pk_mul_f32 v[16:17], v[14:15], v[14:15]
	s_nop 0
	v_pk_mul_f32 v[16:17], v[14:15], v[16:17]
	s_nop 0
	v_pk_fma_f32 v[16:17], v[16:17], s[2:3], v[14:15] op_sel_hi:[1,0,1]
	s_movk_i32 s2, 0x1600
	v_pk_mul_f32 v[16:17], v[16:17], s[24:25] op_sel_hi:[1,0]
	s_nop 0
	v_exp_f32_e32 v16, v16
	v_exp_f32_e32 v17, v17
	s_nop 0
	v_pk_add_f32 v[16:17], v[16:17], 1.0 op_sel_hi:[1,0]
	s_nop 0
	v_rcp_f32_e32 v16, v16
	v_rcp_f32_e32 v17, v17
	s_nop 0
	v_pk_mul_f32 v[14:15], v[14:15], v[16:17]
	s_nop 0
	v_pk_mul_f32 v[10:11], v[10:11], v[14:15]
	s_nop 0
	v_cvt_pk_bf16_f32 v12, v10, v11
	v_mov_b64_e32 v[10:11], s[76:77]
	v_mad_i64_i32 v[10:11], s[58:59], v78, s2, v[10:11]
	v_lshl_add_u64 v[10:11], v[162:163], 1, v[10:11]
	global_store_dwordx2 v[10:11], v[12:13], off offset:8
	s_or_b64 exec, exec, s[12:13]
	s_and_saveexec_b64 s[12:13], s[52:53]
	s_cbranch_execnz .LBB0_493
